# v6 + GEMM K-loop heads pinned at their natural 64B phases (p2align + s_nop)
# baseline (speedup 1.0000x reference)
; template <class Epi, class Sched, bool ALIGN_EPI = false, bool SP2 = false>
; __device__ __forceinline__ void gemm_phase(PG8_LAS unsigned char* lds, const Gemm g, const Sched& S, const Epi& E, const int wid_in) {
;     ...
;         for (int t = 0; t < nt; t += 2) {
;             const bool last = (t == nt - 2);
;             const char* a1 = cA + (size_t)(t + 1) * kstep;
;             const char* a2 = last ? nA : cA + (size_t)(t + 2) * kstep; const char* b2 = last ? nB : cB + (size_t)(t + 2) * kstep;
;             const char* a3 = a2 + kstep; const char* b3 = b2 + kstep;
;     ...
; #pragma unroll
;         for (int a = 0; a < 2; ++a)
; #pragma unroll
;             for (int b = 0; b < 2; ++b)
; #pragma unroll
;                 for (int m = 0; m < 4; ++m)
; #pragma unroll
;                     for (int n = 0; n < 2; ++n) acc[a][b][m][n] = (f32x4){0.f, 0.f, 0.f, 0.f};
;         cur = nxt; cA = nA; cB = nB; ++ui;
.LBB0_148:
	v_mov_b32_e32 v127, 0
	s_andn2_b64 vcc, exec, s[18:19]
	v_mov_b32_e32 v126, v127
	v_mov_b32_e32 v125, v127
	v_mov_b32_e32 v124, v127
	v_mov_b32_e32 v123, v127
	v_mov_b32_e32 v122, v127
	v_mov_b32_e32 v121, v127
	v_mov_b32_e32 v120, v127
	v_mov_b32_e32 v111, v127
	v_mov_b32_e32 v110, v127
	v_mov_b32_e32 v109, v127
	v_mov_b32_e32 v108, v127
	v_mov_b32_e32 v107, v127
	v_mov_b32_e32 v106, v127
	v_mov_b32_e32 v105, v127
	v_mov_b32_e32 v104, v127
	v_mov_b32_e32 v95, v127
	v_mov_b32_e32 v94, v127
	v_mov_b32_e32 v93, v127
	v_mov_b32_e32 v92, v127
	v_mov_b32_e32 v91, v127
	v_mov_b32_e32 v90, v127
	v_mov_b32_e32 v89, v127
	v_mov_b32_e32 v88, v127
	v_mov_b32_e32 v79, v127
	v_mov_b32_e32 v78, v127
	v_mov_b32_e32 v77, v127
	v_mov_b32_e32 v76, v127
	v_mov_b32_e32 v75, v127
	v_mov_b32_e32 v74, v127
	v_mov_b32_e32 v73, v127
	v_mov_b32_e32 v72, v127
	v_mov_b32_e32 v119, v127
	v_mov_b32_e32 v118, v127
	v_mov_b32_e32 v117, v127
	v_mov_b32_e32 v116, v127
	v_mov_b32_e32 v115, v127
	v_mov_b32_e32 v114, v127
	v_mov_b32_e32 v113, v127
	v_mov_b32_e32 v112, v127
	v_mov_b32_e32 v103, v127
	v_mov_b32_e32 v102, v127
	v_mov_b32_e32 v101, v127
	v_mov_b32_e32 v100, v127
	v_mov_b32_e32 v99, v127
	v_mov_b32_e32 v98, v127
	v_mov_b32_e32 v97, v127
	v_mov_b32_e32 v96, v127
	v_mov_b32_e32 v87, v127
	v_mov_b32_e32 v86, v127
	v_mov_b32_e32 v85, v127
	v_mov_b32_e32 v84, v127
	v_mov_b32_e32 v83, v127
	v_mov_b32_e32 v82, v127
	v_mov_b32_e32 v81, v127
	v_mov_b32_e32 v80, v127
	v_mov_b32_e32 v71, v127
	v_mov_b32_e32 v70, v127
	v_mov_b32_e32 v69, v127
	v_mov_b32_e32 v68, v127
	v_mov_b32_e32 v67, v127
	v_mov_b32_e32 v66, v127
	v_mov_b32_e32 v65, v127
	v_mov_b32_e32 v64, v127
	v_mov_b32_e32 v63, v127
	v_mov_b32_e32 v62, v127
	v_mov_b32_e32 v61, v127
	v_mov_b32_e32 v60, v127
	v_mov_b32_e32 v59, v127
	v_mov_b32_e32 v58, v127
	v_mov_b32_e32 v57, v127
	v_mov_b32_e32 v56, v127
	v_mov_b32_e32 v47, v127
	v_mov_b32_e32 v46, v127
	v_mov_b32_e32 v45, v127
	v_mov_b32_e32 v44, v127
	v_mov_b32_e32 v43, v127
	v_mov_b32_e32 v42, v127
	v_mov_b32_e32 v41, v127
	v_mov_b32_e32 v40, v127
	v_mov_b32_e32 v31, v127
	v_mov_b32_e32 v30, v127
	v_mov_b32_e32 v29, v127
	v_mov_b32_e32 v28, v127
	v_mov_b32_e32 v27, v127
	v_mov_b32_e32 v26, v127
	v_mov_b32_e32 v25, v127
	v_mov_b32_e32 v24, v127
	v_mov_b32_e32 v15, v127
	v_mov_b32_e32 v14, v127
	v_mov_b32_e32 v13, v127
	v_mov_b32_e32 v12, v127
	v_mov_b32_e32 v11, v127
	v_mov_b32_e32 v10, v127
	v_mov_b32_e32 v9, v127
	v_mov_b32_e32 v8, v127
	v_mov_b32_e32 v55, v127
	v_mov_b32_e32 v54, v127
	v_mov_b32_e32 v53, v127
	v_mov_b32_e32 v52, v127
	v_mov_b32_e32 v51, v127
	v_mov_b32_e32 v50, v127
	v_mov_b32_e32 v49, v127
	v_mov_b32_e32 v48, v127
	v_mov_b32_e32 v39, v127
	v_mov_b32_e32 v38, v127
	v_mov_b32_e32 v37, v127
	v_mov_b32_e32 v36, v127
	v_mov_b32_e32 v35, v127
	v_mov_b32_e32 v34, v127
	v_mov_b32_e32 v33, v127
	v_mov_b32_e32 v32, v127
	v_mov_b32_e32 v23, v127
	v_mov_b32_e32 v22, v127
	v_mov_b32_e32 v21, v127
	v_mov_b32_e32 v20, v127
	v_mov_b32_e32 v19, v127
	v_mov_b32_e32 v18, v127
	v_mov_b32_e32 v17, v127
	v_mov_b32_e32 v16, v127
	v_mov_b32_e32 v7, v127
	v_mov_b32_e32 v6, v127
	v_mov_b32_e32 v5, v127
	v_mov_b32_e32 v4, v127
	v_mov_b32_e32 v3, v127
	v_mov_b32_e32 v2, v127
	v_mov_b32_e32 v1, v127
	v_mov_b32_e32 v0, v127
	s_cbranch_vccnz .LBB0_151
	s_add_u32 s8, s60, 0x80
	s_addc_u32 s9, s61, 0
	s_add_u32 s5, s58, 0x100
	v_mov_b32_e32 v0, 0
	s_addc_u32 s33, s59, 0
	s_mov_b32 s58, 0
	v_mov_b32_e32 v1, v0
	v_mov_b32_e32 v2, v0
	v_mov_b32_e32 v3, v0
	v_mov_b32_e32 v4, v0
	v_mov_b32_e32 v5, v0
	v_mov_b32_e32 v6, v0
	v_mov_b32_e32 v7, v0
	v_mov_b32_e32 v16, v0
	v_mov_b32_e32 v17, v0
	v_mov_b32_e32 v18, v0
	v_mov_b32_e32 v19, v0
	v_mov_b32_e32 v20, v0
	v_mov_b32_e32 v21, v0
	v_mov_b32_e32 v22, v0
	v_mov_b32_e32 v23, v0
	v_mov_b32_e32 v32, v0
	v_mov_b32_e32 v33, v0
	v_mov_b32_e32 v34, v0
	v_mov_b32_e32 v35, v0
	v_mov_b32_e32 v36, v0
	v_mov_b32_e32 v37, v0
	v_mov_b32_e32 v38, v0
	v_mov_b32_e32 v39, v0
	v_mov_b32_e32 v48, v0
	v_mov_b32_e32 v49, v0
	v_mov_b32_e32 v50, v0
	v_mov_b32_e32 v51, v0
	v_mov_b32_e32 v52, v0
	v_mov_b32_e32 v53, v0
	v_mov_b32_e32 v54, v0
	v_mov_b32_e32 v55, v0
	v_mov_b32_e32 v8, v0
	v_mov_b32_e32 v9, v0
	v_mov_b32_e32 v10, v0
	v_mov_b32_e32 v11, v0
	v_mov_b32_e32 v12, v0
	v_mov_b32_e32 v13, v0
	v_mov_b32_e32 v14, v0
	v_mov_b32_e32 v15, v0
	v_mov_b32_e32 v24, v0
	v_mov_b32_e32 v25, v0
	v_mov_b32_e32 v26, v0
	v_mov_b32_e32 v27, v0
	v_mov_b32_e32 v28, v0
	v_mov_b32_e32 v29, v0
	v_mov_b32_e32 v30, v0
	v_mov_b32_e32 v31, v0
	v_mov_b32_e32 v40, v0
	v_mov_b32_e32 v41, v0
	v_mov_b32_e32 v42, v0
	v_mov_b32_e32 v43, v0
	v_mov_b32_e32 v44, v0
	v_mov_b32_e32 v45, v0
	v_mov_b32_e32 v46, v0
	v_mov_b32_e32 v47, v0
	v_mov_b32_e32 v56, v0
	v_mov_b32_e32 v57, v0
	v_mov_b32_e32 v58, v0
	v_mov_b32_e32 v59, v0
	v_mov_b32_e32 v60, v0
	v_mov_b32_e32 v61, v0
	v_mov_b32_e32 v62, v0
	v_mov_b32_e32 v63, v0
	v_mov_b32_e32 v64, v0
	v_mov_b32_e32 v65, v0
	v_mov_b32_e32 v66, v0
	v_mov_b32_e32 v67, v0
	v_mov_b32_e32 v68, v0
	v_mov_b32_e32 v69, v0
	v_mov_b32_e32 v70, v0
	v_mov_b32_e32 v71, v0
	v_mov_b32_e32 v80, v0
	v_mov_b32_e32 v81, v0
	v_mov_b32_e32 v82, v0
	v_mov_b32_e32 v83, v0
	v_mov_b32_e32 v84, v0
	v_mov_b32_e32 v85, v0
	v_mov_b32_e32 v86, v0
	v_mov_b32_e32 v87, v0
	v_mov_b32_e32 v96, v0
	v_mov_b32_e32 v97, v0
	v_mov_b32_e32 v98, v0
	v_mov_b32_e32 v99, v0
	v_mov_b32_e32 v100, v0
	v_mov_b32_e32 v101, v0
	v_mov_b32_e32 v102, v0
	v_mov_b32_e32 v103, v0
	v_mov_b32_e32 v112, v0
	v_mov_b32_e32 v113, v0
	v_mov_b32_e32 v114, v0
	v_mov_b32_e32 v115, v0
	v_mov_b32_e32 v116, v0
	v_mov_b32_e32 v117, v0
	v_mov_b32_e32 v118, v0
	v_mov_b32_e32 v119, v0
	v_mov_b32_e32 v72, v0
	v_mov_b32_e32 v73, v0
	v_mov_b32_e32 v74, v0
	v_mov_b32_e32 v75, v0
	v_mov_b32_e32 v76, v0
	v_mov_b32_e32 v77, v0
	v_mov_b32_e32 v78, v0
	v_mov_b32_e32 v79, v0
	v_mov_b32_e32 v88, v0
	v_mov_b32_e32 v89, v0
	v_mov_b32_e32 v90, v0
	v_mov_b32_e32 v91, v0
	v_mov_b32_e32 v92, v0
	v_mov_b32_e32 v93, v0
	v_mov_b32_e32 v94, v0
	v_mov_b32_e32 v95, v0
	v_mov_b32_e32 v104, v0
	v_mov_b32_e32 v105, v0
	v_mov_b32_e32 v106, v0
	v_mov_b32_e32 v107, v0
	v_mov_b32_e32 v108, v0
	v_mov_b32_e32 v109, v0
	v_mov_b32_e32 v110, v0
	v_mov_b32_e32 v111, v0
	v_mov_b32_e32 v120, v0
	v_mov_b32_e32 v121, v0
	v_mov_b32_e32 v122, v0
	v_mov_b32_e32 v123, v0
	v_mov_b32_e32 v124, v0
	v_mov_b32_e32 v125, v0
	v_mov_b32_e32 v126, v0
	v_mov_b32_e32 v127, v0
	.p2align 6
	s_nop 0
	s_nop 0
	s_nop 0
	s_nop 0
	s_nop 0
	s_nop 0
	s_nop 0
	s_nop 0
	s_nop 0
	s_nop 0
	s_nop 0
	s_nop 0

; template <class Epi, class Sched, bool ALIGN_EPI = false, bool SP2 = false>
; __device__ __forceinline__ void gemm_phase(PG8_LAS unsigned char* lds, const Gemm g, const Sched& S, const Epi& E, const int wid_in) {
;     ...
;         for (int t = 0; t < nt; t += 2) {
;             const bool last = (t == nt - 2);
;             const char* a1 = cA + (size_t)(t + 1) * kstep;
;             const char* a2 = last ? nA : cA + (size_t)(t + 2) * kstep; const char* b2 = last ? nB : cB + (size_t)(t + 2) * kstep;
;             const char* a3 = a2 + kstep; const char* b3 = b2 + kstep;
;     ...
; #pragma unroll
;         for (int a = 0; a < 2; ++a)
; #pragma unroll
;             for (int b = 0; b < 2; ++b)
; #pragma unroll
;                 for (int m = 0; m < 4; ++m)
; #pragma unroll
;                     for (int n = 0; n < 2; ++n) acc[a][b][m][n] = (f32x4){0.f, 0.f, 0.f, 0.f};
;         cur = nxt; cA = nA; cB = nB; ++ui;
.LBB0_785:
	v_mov_b32_e32 v123, 0
	s_andn2_b64 vcc, exec, s[26:27]
	v_mov_b32_e32 v122, v123
	v_mov_b32_e32 v121, v123
	v_mov_b32_e32 v120, v123
	v_mov_b32_e32 v127, v123
	v_mov_b32_e32 v126, v123
	v_mov_b32_e32 v125, v123
	v_mov_b32_e32 v124, v123
	v_mov_b32_e32 v111, v123
	v_mov_b32_e32 v110, v123
	v_mov_b32_e32 v109, v123
	v_mov_b32_e32 v108, v123
	v_mov_b32_e32 v107, v123
	v_mov_b32_e32 v106, v123
	v_mov_b32_e32 v105, v123
	v_mov_b32_e32 v104, v123
	v_mov_b32_e32 v95, v123
	v_mov_b32_e32 v94, v123
	v_mov_b32_e32 v93, v123
	v_mov_b32_e32 v92, v123
	v_mov_b32_e32 v91, v123
	v_mov_b32_e32 v90, v123
	v_mov_b32_e32 v89, v123
	v_mov_b32_e32 v88, v123
	v_mov_b32_e32 v79, v123
	v_mov_b32_e32 v78, v123
	v_mov_b32_e32 v77, v123
	v_mov_b32_e32 v76, v123
	v_mov_b32_e32 v75, v123
	v_mov_b32_e32 v74, v123
	v_mov_b32_e32 v73, v123
	v_mov_b32_e32 v72, v123
	v_mov_b32_e32 v119, v123
	v_mov_b32_e32 v118, v123
	v_mov_b32_e32 v117, v123
	v_mov_b32_e32 v116, v123
	v_mov_b32_e32 v115, v123
	v_mov_b32_e32 v114, v123
	v_mov_b32_e32 v113, v123
	v_mov_b32_e32 v112, v123
	v_mov_b32_e32 v103, v123
	v_mov_b32_e32 v102, v123
	v_mov_b32_e32 v101, v123
	v_mov_b32_e32 v100, v123
	v_mov_b32_e32 v99, v123
	v_mov_b32_e32 v98, v123
	v_mov_b32_e32 v97, v123
	v_mov_b32_e32 v96, v123
	v_mov_b32_e32 v87, v123
	v_mov_b32_e32 v86, v123
	v_mov_b32_e32 v85, v123
	v_mov_b32_e32 v84, v123
	v_mov_b32_e32 v83, v123
	v_mov_b32_e32 v82, v123
	v_mov_b32_e32 v81, v123
	v_mov_b32_e32 v80, v123
	v_mov_b32_e32 v71, v123
	v_mov_b32_e32 v70, v123
	v_mov_b32_e32 v69, v123
	v_mov_b32_e32 v68, v123
	v_mov_b32_e32 v67, v123
	v_mov_b32_e32 v66, v123
	v_mov_b32_e32 v65, v123
	v_mov_b32_e32 v64, v123
	v_mov_b32_e32 v63, v123
	v_mov_b32_e32 v62, v123
	v_mov_b32_e32 v61, v123
	v_mov_b32_e32 v60, v123
	v_mov_b32_e32 v59, v123
	v_mov_b32_e32 v58, v123
	v_mov_b32_e32 v57, v123
	v_mov_b32_e32 v56, v123
	v_mov_b32_e32 v47, v123
	v_mov_b32_e32 v46, v123
	v_mov_b32_e32 v45, v123
	v_mov_b32_e32 v44, v123
	v_mov_b32_e32 v43, v123
	v_mov_b32_e32 v42, v123
	v_mov_b32_e32 v41, v123
	v_mov_b32_e32 v40, v123
	v_mov_b32_e32 v31, v123
	v_mov_b32_e32 v30, v123
	v_mov_b32_e32 v29, v123
	v_mov_b32_e32 v28, v123
	v_mov_b32_e32 v27, v123
	v_mov_b32_e32 v26, v123
	v_mov_b32_e32 v25, v123
	v_mov_b32_e32 v24, v123
	v_mov_b32_e32 v15, v123
	v_mov_b32_e32 v14, v123
	v_mov_b32_e32 v13, v123
	v_mov_b32_e32 v12, v123
	v_mov_b32_e32 v11, v123
	v_mov_b32_e32 v10, v123
	v_mov_b32_e32 v9, v123
	v_mov_b32_e32 v8, v123
	v_mov_b32_e32 v55, v123
	v_mov_b32_e32 v54, v123
	v_mov_b32_e32 v53, v123
	v_mov_b32_e32 v52, v123
	v_mov_b32_e32 v51, v123
	v_mov_b32_e32 v50, v123
	v_mov_b32_e32 v49, v123
	v_mov_b32_e32 v48, v123
	v_mov_b32_e32 v39, v123
	v_mov_b32_e32 v38, v123
	v_mov_b32_e32 v37, v123
	v_mov_b32_e32 v36, v123
	v_mov_b32_e32 v35, v123
	v_mov_b32_e32 v34, v123
	v_mov_b32_e32 v33, v123
	v_mov_b32_e32 v32, v123
	v_mov_b32_e32 v23, v123
	v_mov_b32_e32 v22, v123
	v_mov_b32_e32 v21, v123
	v_mov_b32_e32 v20, v123
	v_mov_b32_e32 v19, v123
	v_mov_b32_e32 v18, v123
	v_mov_b32_e32 v17, v123
	v_mov_b32_e32 v16, v123
	v_mov_b32_e32 v7, v123
	v_mov_b32_e32 v6, v123
	v_mov_b32_e32 v5, v123
	v_mov_b32_e32 v4, v123
	v_mov_b32_e32 v3, v123
	v_mov_b32_e32 v2, v123
	v_mov_b32_e32 v1, v123
	v_mov_b32_e32 v0, v123
	s_cbranch_vccnz .LBB0_788
	s_add_u32 s56, s56, 0x80
	s_addc_u32 s57, s57, 0
	s_add_u32 s73, s58, 0x100
	v_mov_b32_e32 v0, 0
	s_addc_u32 s76, s59, 0
	s_mov_b32 s58, 0
	v_mov_b32_e32 v1, v0
	v_mov_b32_e32 v2, v0
	v_mov_b32_e32 v3, v0
	v_mov_b32_e32 v4, v0
	v_mov_b32_e32 v5, v0
	v_mov_b32_e32 v6, v0
	v_mov_b32_e32 v7, v0
	v_mov_b32_e32 v16, v0
	v_mov_b32_e32 v17, v0
	v_mov_b32_e32 v18, v0
	v_mov_b32_e32 v19, v0
	v_mov_b32_e32 v20, v0
	v_mov_b32_e32 v21, v0
	v_mov_b32_e32 v22, v0
	v_mov_b32_e32 v23, v0
	v_mov_b32_e32 v32, v0
	v_mov_b32_e32 v33, v0
	v_mov_b32_e32 v34, v0
	v_mov_b32_e32 v35, v0
	v_mov_b32_e32 v36, v0
	v_mov_b32_e32 v37, v0
	v_mov_b32_e32 v38, v0
	v_mov_b32_e32 v39, v0
	v_mov_b32_e32 v48, v0
	v_mov_b32_e32 v49, v0
	v_mov_b32_e32 v50, v0
	v_mov_b32_e32 v51, v0
	v_mov_b32_e32 v52, v0
	v_mov_b32_e32 v53, v0
	v_mov_b32_e32 v54, v0
	v_mov_b32_e32 v55, v0
	v_mov_b32_e32 v8, v0
	v_mov_b32_e32 v9, v0
	v_mov_b32_e32 v10, v0
	v_mov_b32_e32 v11, v0
	v_mov_b32_e32 v12, v0
	v_mov_b32_e32 v13, v0
	v_mov_b32_e32 v14, v0
	v_mov_b32_e32 v15, v0
	v_mov_b32_e32 v24, v0
	v_mov_b32_e32 v25, v0
	v_mov_b32_e32 v26, v0
	v_mov_b32_e32 v27, v0
	v_mov_b32_e32 v28, v0
	v_mov_b32_e32 v29, v0
	v_mov_b32_e32 v30, v0
	v_mov_b32_e32 v31, v0
	v_mov_b32_e32 v40, v0
	v_mov_b32_e32 v41, v0
	v_mov_b32_e32 v42, v0
	v_mov_b32_e32 v43, v0
	v_mov_b32_e32 v44, v0
	v_mov_b32_e32 v45, v0
	v_mov_b32_e32 v46, v0
	v_mov_b32_e32 v47, v0
	v_mov_b32_e32 v56, v0
	v_mov_b32_e32 v57, v0
	v_mov_b32_e32 v58, v0
	v_mov_b32_e32 v59, v0
	v_mov_b32_e32 v60, v0
	v_mov_b32_e32 v61, v0
	v_mov_b32_e32 v62, v0
	v_mov_b32_e32 v63, v0
	v_mov_b32_e32 v64, v0
	v_mov_b32_e32 v65, v0
	v_mov_b32_e32 v66, v0
	v_mov_b32_e32 v67, v0
	v_mov_b32_e32 v68, v0
	v_mov_b32_e32 v69, v0
	v_mov_b32_e32 v70, v0
	v_mov_b32_e32 v71, v0
	v_mov_b32_e32 v80, v0
	v_mov_b32_e32 v81, v0
	v_mov_b32_e32 v82, v0
	v_mov_b32_e32 v83, v0
	v_mov_b32_e32 v84, v0
	v_mov_b32_e32 v85, v0
	v_mov_b32_e32 v86, v0
	v_mov_b32_e32 v87, v0
	v_mov_b32_e32 v96, v0
	v_mov_b32_e32 v97, v0
	v_mov_b32_e32 v98, v0
	v_mov_b32_e32 v99, v0
	v_mov_b32_e32 v100, v0
	v_mov_b32_e32 v101, v0
	v_mov_b32_e32 v102, v0
	v_mov_b32_e32 v103, v0
	v_mov_b32_e32 v112, v0
	v_mov_b32_e32 v113, v0
	v_mov_b32_e32 v114, v0
	v_mov_b32_e32 v115, v0
	v_mov_b32_e32 v116, v0
	v_mov_b32_e32 v117, v0
	v_mov_b32_e32 v118, v0
	v_mov_b32_e32 v119, v0
	v_mov_b32_e32 v72, v0
	v_mov_b32_e32 v73, v0
	v_mov_b32_e32 v74, v0
	v_mov_b32_e32 v75, v0
	v_mov_b32_e32 v76, v0
	v_mov_b32_e32 v77, v0
	v_mov_b32_e32 v78, v0
	v_mov_b32_e32 v79, v0
	v_mov_b32_e32 v88, v0
	v_mov_b32_e32 v89, v0
	v_mov_b32_e32 v90, v0
	v_mov_b32_e32 v91, v0
	v_mov_b32_e32 v92, v0
	v_mov_b32_e32 v93, v0
	v_mov_b32_e32 v94, v0
	v_mov_b32_e32 v95, v0
	v_mov_b32_e32 v104, v0
	v_mov_b32_e32 v105, v0
	v_mov_b32_e32 v106, v0
	v_mov_b32_e32 v107, v0
	v_mov_b32_e32 v108, v0
	v_mov_b32_e32 v109, v0
	v_mov_b32_e32 v110, v0
	v_mov_b32_e32 v111, v0
	v_mov_b32_e32 v124, v0
	v_mov_b32_e32 v125, v0
	v_mov_b32_e32 v126, v0
	v_mov_b32_e32 v127, v0
	v_mov_b32_e32 v120, v0
	v_mov_b32_e32 v121, v0
	v_mov_b32_e32 v122, v0
	v_mov_b32_e32 v123, v0
	.p2align 6
	s_nop 0
	s_nop 0

; template <class Epi, class Sched, bool ALIGN_EPI = false, bool SP2 = false>
; __device__ __forceinline__ void gemm_phase(PG8_LAS unsigned char* lds, const Gemm g, const Sched& S, const Epi& E, const int wid_in) {
;     ...
;         for (int t = 0; t < nt; t += 2) {
;             const bool last = (t == nt - 2);
;             const char* a1 = cA + (size_t)(t + 1) * kstep;
;             const char* a2 = last ? nA : cA + (size_t)(t + 2) * kstep; const char* b2 = last ? nB : cB + (size_t)(t + 2) * kstep;
;             const char* a3 = a2 + kstep; const char* b3 = b2 + kstep;
;     ...
; #pragma unroll
;         for (int a = 0; a < 2; ++a)
; #pragma unroll
;             for (int b = 0; b < 2; ++b)
; #pragma unroll
;                 for (int m = 0; m < 4; ++m)
; #pragma unroll
;                     for (int n = 0; n < 2; ++n) acc[a][b][m][n] = (f32x4){0.f, 0.f, 0.f, 0.f};
;         cur = nxt; cA = nA; cB = nB; ++ui;
.LBB0_814:
	v_mov_b32_e32 v123, 0
	s_andn2_b64 vcc, exec, s[24:25]
	v_mov_b32_e32 v122, v123
	v_mov_b32_e32 v121, v123
	v_mov_b32_e32 v120, v123
	v_mov_b32_e32 v127, v123
	v_mov_b32_e32 v126, v123
	v_mov_b32_e32 v125, v123
	v_mov_b32_e32 v124, v123
	v_mov_b32_e32 v111, v123
	v_mov_b32_e32 v110, v123
	v_mov_b32_e32 v109, v123
	v_mov_b32_e32 v108, v123
	v_mov_b32_e32 v107, v123
	v_mov_b32_e32 v106, v123
	v_mov_b32_e32 v105, v123
	v_mov_b32_e32 v104, v123
	v_mov_b32_e32 v95, v123
	v_mov_b32_e32 v94, v123
	v_mov_b32_e32 v93, v123
	v_mov_b32_e32 v92, v123
	v_mov_b32_e32 v91, v123
	v_mov_b32_e32 v90, v123
	v_mov_b32_e32 v89, v123
	v_mov_b32_e32 v88, v123
	v_mov_b32_e32 v79, v123
	v_mov_b32_e32 v78, v123
	v_mov_b32_e32 v77, v123
	v_mov_b32_e32 v76, v123
	v_mov_b32_e32 v75, v123
	v_mov_b32_e32 v74, v123
	v_mov_b32_e32 v73, v123
	v_mov_b32_e32 v72, v123
	v_mov_b32_e32 v119, v123
	v_mov_b32_e32 v118, v123
	v_mov_b32_e32 v117, v123
	v_mov_b32_e32 v116, v123
	v_mov_b32_e32 v115, v123
	v_mov_b32_e32 v114, v123
	v_mov_b32_e32 v113, v123
	v_mov_b32_e32 v112, v123
	v_mov_b32_e32 v103, v123
	v_mov_b32_e32 v102, v123
	v_mov_b32_e32 v101, v123
	v_mov_b32_e32 v100, v123
	v_mov_b32_e32 v99, v123
	v_mov_b32_e32 v98, v123
	v_mov_b32_e32 v97, v123
	v_mov_b32_e32 v96, v123
	v_mov_b32_e32 v87, v123
	v_mov_b32_e32 v86, v123
	v_mov_b32_e32 v85, v123
	v_mov_b32_e32 v84, v123
	v_mov_b32_e32 v83, v123
	v_mov_b32_e32 v82, v123
	v_mov_b32_e32 v81, v123
	v_mov_b32_e32 v80, v123
	v_mov_b32_e32 v71, v123
	v_mov_b32_e32 v70, v123
	v_mov_b32_e32 v69, v123
	v_mov_b32_e32 v68, v123
	v_mov_b32_e32 v67, v123
	v_mov_b32_e32 v66, v123
	v_mov_b32_e32 v65, v123
	v_mov_b32_e32 v64, v123
	v_mov_b32_e32 v63, v123
	v_mov_b32_e32 v62, v123
	v_mov_b32_e32 v61, v123
	v_mov_b32_e32 v60, v123
	v_mov_b32_e32 v59, v123
	v_mov_b32_e32 v58, v123
	v_mov_b32_e32 v57, v123
	v_mov_b32_e32 v56, v123
	v_mov_b32_e32 v47, v123
	v_mov_b32_e32 v46, v123
	v_mov_b32_e32 v45, v123
	v_mov_b32_e32 v44, v123
	v_mov_b32_e32 v43, v123
	v_mov_b32_e32 v42, v123
	v_mov_b32_e32 v41, v123
	v_mov_b32_e32 v40, v123
	v_mov_b32_e32 v31, v123
	v_mov_b32_e32 v30, v123
	v_mov_b32_e32 v29, v123
	v_mov_b32_e32 v28, v123
	v_mov_b32_e32 v27, v123
	v_mov_b32_e32 v26, v123
	v_mov_b32_e32 v25, v123
	v_mov_b32_e32 v24, v123
	v_mov_b32_e32 v15, v123
	v_mov_b32_e32 v14, v123
	v_mov_b32_e32 v13, v123
	v_mov_b32_e32 v12, v123
	v_mov_b32_e32 v11, v123
	v_mov_b32_e32 v10, v123
	v_mov_b32_e32 v9, v123
	v_mov_b32_e32 v8, v123
	v_mov_b32_e32 v55, v123
	v_mov_b32_e32 v54, v123
	v_mov_b32_e32 v53, v123
	v_mov_b32_e32 v52, v123
	v_mov_b32_e32 v51, v123
	v_mov_b32_e32 v50, v123
	v_mov_b32_e32 v49, v123
	v_mov_b32_e32 v48, v123
	v_mov_b32_e32 v39, v123
	v_mov_b32_e32 v38, v123
	v_mov_b32_e32 v37, v123
	v_mov_b32_e32 v36, v123
	v_mov_b32_e32 v35, v123
	v_mov_b32_e32 v34, v123
	v_mov_b32_e32 v33, v123
	v_mov_b32_e32 v32, v123
	v_mov_b32_e32 v23, v123
	v_mov_b32_e32 v22, v123
	v_mov_b32_e32 v21, v123
	v_mov_b32_e32 v20, v123
	v_mov_b32_e32 v19, v123
	v_mov_b32_e32 v18, v123
	v_mov_b32_e32 v17, v123
	v_mov_b32_e32 v16, v123
	v_mov_b32_e32 v7, v123
	v_mov_b32_e32 v6, v123
	v_mov_b32_e32 v5, v123
	v_mov_b32_e32 v4, v123
	v_mov_b32_e32 v3, v123
	v_mov_b32_e32 v2, v123
	v_mov_b32_e32 v1, v123
	v_mov_b32_e32 v0, v123
	s_cbranch_vccnz .LBB0_817
	s_add_u32 s54, s54, 0x80
	s_addc_u32 s55, s55, 0
	s_add_u32 s72, s56, 0x100
	v_mov_b32_e32 v0, 0
	s_addc_u32 s73, s57, 0
	s_mov_b32 s56, 0
	v_mov_b32_e32 v1, v0
	v_mov_b32_e32 v2, v0
	v_mov_b32_e32 v3, v0
	v_mov_b32_e32 v4, v0
	v_mov_b32_e32 v5, v0
	v_mov_b32_e32 v6, v0
	v_mov_b32_e32 v7, v0
	v_mov_b32_e32 v16, v0
	v_mov_b32_e32 v17, v0
	v_mov_b32_e32 v18, v0
	v_mov_b32_e32 v19, v0
	v_mov_b32_e32 v20, v0
	v_mov_b32_e32 v21, v0
	v_mov_b32_e32 v22, v0
	v_mov_b32_e32 v23, v0
	v_mov_b32_e32 v32, v0
	v_mov_b32_e32 v33, v0
	v_mov_b32_e32 v34, v0
	v_mov_b32_e32 v35, v0
	v_mov_b32_e32 v36, v0
	v_mov_b32_e32 v37, v0
	v_mov_b32_e32 v38, v0
	v_mov_b32_e32 v39, v0
	v_mov_b32_e32 v48, v0
	v_mov_b32_e32 v49, v0
	v_mov_b32_e32 v50, v0
	v_mov_b32_e32 v51, v0
	v_mov_b32_e32 v52, v0
	v_mov_b32_e32 v53, v0
	v_mov_b32_e32 v54, v0
	v_mov_b32_e32 v55, v0
	v_mov_b32_e32 v8, v0
	v_mov_b32_e32 v9, v0
	v_mov_b32_e32 v10, v0
	v_mov_b32_e32 v11, v0
	v_mov_b32_e32 v12, v0
	v_mov_b32_e32 v13, v0
	v_mov_b32_e32 v14, v0
	v_mov_b32_e32 v15, v0
	v_mov_b32_e32 v24, v0
	v_mov_b32_e32 v25, v0
	v_mov_b32_e32 v26, v0
	v_mov_b32_e32 v27, v0
	v_mov_b32_e32 v28, v0
	v_mov_b32_e32 v29, v0
	v_mov_b32_e32 v30, v0
	v_mov_b32_e32 v31, v0
	v_mov_b32_e32 v40, v0
	v_mov_b32_e32 v41, v0
	v_mov_b32_e32 v42, v0
	v_mov_b32_e32 v43, v0
	v_mov_b32_e32 v44, v0
	v_mov_b32_e32 v45, v0
	v_mov_b32_e32 v46, v0
	v_mov_b32_e32 v47, v0
	v_mov_b32_e32 v56, v0
	v_mov_b32_e32 v57, v0
	v_mov_b32_e32 v58, v0
	v_mov_b32_e32 v59, v0
	v_mov_b32_e32 v60, v0
	v_mov_b32_e32 v61, v0
	v_mov_b32_e32 v62, v0
	v_mov_b32_e32 v63, v0
	v_mov_b32_e32 v64, v0
	v_mov_b32_e32 v65, v0
	v_mov_b32_e32 v66, v0
	v_mov_b32_e32 v67, v0
	v_mov_b32_e32 v68, v0
	v_mov_b32_e32 v69, v0
	v_mov_b32_e32 v70, v0
	v_mov_b32_e32 v71, v0
	v_mov_b32_e32 v80, v0
	v_mov_b32_e32 v81, v0
	v_mov_b32_e32 v82, v0
	v_mov_b32_e32 v83, v0
	v_mov_b32_e32 v84, v0
	v_mov_b32_e32 v85, v0
	v_mov_b32_e32 v86, v0
	v_mov_b32_e32 v87, v0
	v_mov_b32_e32 v96, v0
	v_mov_b32_e32 v97, v0
	v_mov_b32_e32 v98, v0
	v_mov_b32_e32 v99, v0
	v_mov_b32_e32 v100, v0
	v_mov_b32_e32 v101, v0
	v_mov_b32_e32 v102, v0
	v_mov_b32_e32 v103, v0
	v_mov_b32_e32 v112, v0
	v_mov_b32_e32 v113, v0
	v_mov_b32_e32 v114, v0
	v_mov_b32_e32 v115, v0
	v_mov_b32_e32 v116, v0
	v_mov_b32_e32 v117, v0
	v_mov_b32_e32 v118, v0
	v_mov_b32_e32 v119, v0
	v_mov_b32_e32 v72, v0
	v_mov_b32_e32 v73, v0
	v_mov_b32_e32 v74, v0
	v_mov_b32_e32 v75, v0
	v_mov_b32_e32 v76, v0
	v_mov_b32_e32 v77, v0
	v_mov_b32_e32 v78, v0
	v_mov_b32_e32 v79, v0
	v_mov_b32_e32 v88, v0
	v_mov_b32_e32 v89, v0
	v_mov_b32_e32 v90, v0
	v_mov_b32_e32 v91, v0
	v_mov_b32_e32 v92, v0
	v_mov_b32_e32 v93, v0
	v_mov_b32_e32 v94, v0
	v_mov_b32_e32 v95, v0
	v_mov_b32_e32 v104, v0
	v_mov_b32_e32 v105, v0
	v_mov_b32_e32 v106, v0
	v_mov_b32_e32 v107, v0
	v_mov_b32_e32 v108, v0
	v_mov_b32_e32 v109, v0
	v_mov_b32_e32 v110, v0
	v_mov_b32_e32 v111, v0
	v_mov_b32_e32 v124, v0
	v_mov_b32_e32 v125, v0
	v_mov_b32_e32 v126, v0
	v_mov_b32_e32 v127, v0
	v_mov_b32_e32 v120, v0
	v_mov_b32_e32 v121, v0
	v_mov_b32_e32 v122, v0
	v_mov_b32_e32 v123, v0
	.p2align 6
	s_nop 0
	s_nop 0

; template <class Epi, class Sched, bool ALIGN_EPI = false, bool SP2 = false>
; __device__ __forceinline__ void gemm_phase(PG8_LAS unsigned char* lds, const Gemm g, const Sched& S, const Epi& E, const int wid_in) {
;     ...
;         for (int t = 0; t < nt; t += 2) {
;             const bool last = (t == nt - 2);
;             const char* a1 = cA + (size_t)(t + 1) * kstep;
;             const char* a2 = last ? nA : cA + (size_t)(t + 2) * kstep; const char* b2 = last ? nB : cB + (size_t)(t + 2) * kstep;
;             const char* a3 = a2 + kstep; const char* b3 = b2 + kstep;
;     ...
; #pragma unroll
;         for (int a = 0; a < 2; ++a)
; #pragma unroll
;             for (int b = 0; b < 2; ++b)
; #pragma unroll
;                 for (int m = 0; m < 4; ++m)
; #pragma unroll
;                     for (int n = 0; n < 2; ++n) acc[a][b][m][n] = (f32x4){0.f, 0.f, 0.f, 0.f};
;         cur = nxt; cA = nA; cB = nB; ++ui;
.LBB0_897:
	v_mov_b32_e32 v123, 0
	s_andn2_b64 vcc, exec, s[46:47]
	v_mov_b32_e32 v122, v123
	v_mov_b32_e32 v121, v123
	v_mov_b32_e32 v120, v123
	v_mov_b32_e32 v127, v123
	v_mov_b32_e32 v126, v123
	v_mov_b32_e32 v125, v123
	v_mov_b32_e32 v124, v123
	v_mov_b32_e32 v111, v123
	v_mov_b32_e32 v110, v123
	v_mov_b32_e32 v109, v123
	v_mov_b32_e32 v108, v123
	v_mov_b32_e32 v107, v123
	v_mov_b32_e32 v106, v123
	v_mov_b32_e32 v105, v123
	v_mov_b32_e32 v104, v123
	v_mov_b32_e32 v95, v123
	v_mov_b32_e32 v94, v123
	v_mov_b32_e32 v93, v123
	v_mov_b32_e32 v92, v123
	v_mov_b32_e32 v91, v123
	v_mov_b32_e32 v90, v123
	v_mov_b32_e32 v89, v123
	v_mov_b32_e32 v88, v123
	v_mov_b32_e32 v79, v123
	v_mov_b32_e32 v78, v123
	v_mov_b32_e32 v77, v123
	v_mov_b32_e32 v76, v123
	v_mov_b32_e32 v75, v123
	v_mov_b32_e32 v74, v123
	v_mov_b32_e32 v73, v123
	v_mov_b32_e32 v72, v123
	v_mov_b32_e32 v119, v123
	v_mov_b32_e32 v118, v123
	v_mov_b32_e32 v117, v123
	v_mov_b32_e32 v116, v123
	v_mov_b32_e32 v115, v123
	v_mov_b32_e32 v114, v123
	v_mov_b32_e32 v113, v123
	v_mov_b32_e32 v112, v123
	v_mov_b32_e32 v103, v123
	v_mov_b32_e32 v102, v123
	v_mov_b32_e32 v101, v123
	v_mov_b32_e32 v100, v123
	v_mov_b32_e32 v99, v123
	v_mov_b32_e32 v98, v123
	v_mov_b32_e32 v97, v123
	v_mov_b32_e32 v96, v123
	v_mov_b32_e32 v87, v123
	v_mov_b32_e32 v86, v123
	v_mov_b32_e32 v85, v123
	v_mov_b32_e32 v84, v123
	v_mov_b32_e32 v83, v123
	v_mov_b32_e32 v82, v123
	v_mov_b32_e32 v81, v123
	v_mov_b32_e32 v80, v123
	v_mov_b32_e32 v71, v123
	v_mov_b32_e32 v70, v123
	v_mov_b32_e32 v69, v123
	v_mov_b32_e32 v68, v123
	v_mov_b32_e32 v67, v123
	v_mov_b32_e32 v66, v123
	v_mov_b32_e32 v65, v123
	v_mov_b32_e32 v64, v123
	v_mov_b32_e32 v63, v123
	v_mov_b32_e32 v62, v123
	v_mov_b32_e32 v61, v123
	v_mov_b32_e32 v60, v123
	v_mov_b32_e32 v59, v123
	v_mov_b32_e32 v58, v123
	v_mov_b32_e32 v57, v123
	v_mov_b32_e32 v56, v123
	v_mov_b32_e32 v47, v123
	v_mov_b32_e32 v46, v123
	v_mov_b32_e32 v45, v123
	v_mov_b32_e32 v44, v123
	v_mov_b32_e32 v43, v123
	v_mov_b32_e32 v42, v123
	v_mov_b32_e32 v41, v123
	v_mov_b32_e32 v40, v123
	v_mov_b32_e32 v31, v123
	v_mov_b32_e32 v30, v123
	v_mov_b32_e32 v29, v123
	v_mov_b32_e32 v28, v123
	v_mov_b32_e32 v27, v123
	v_mov_b32_e32 v26, v123
	v_mov_b32_e32 v25, v123
	v_mov_b32_e32 v24, v123
	v_mov_b32_e32 v15, v123
	v_mov_b32_e32 v14, v123
	v_mov_b32_e32 v13, v123
	v_mov_b32_e32 v12, v123
	v_mov_b32_e32 v11, v123
	v_mov_b32_e32 v10, v123
	v_mov_b32_e32 v9, v123
	v_mov_b32_e32 v8, v123
	v_mov_b32_e32 v55, v123
	v_mov_b32_e32 v54, v123
	v_mov_b32_e32 v53, v123
	v_mov_b32_e32 v52, v123
	v_mov_b32_e32 v51, v123
	v_mov_b32_e32 v50, v123
	v_mov_b32_e32 v49, v123
	v_mov_b32_e32 v48, v123
	v_mov_b32_e32 v39, v123
	v_mov_b32_e32 v38, v123
	v_mov_b32_e32 v37, v123
	v_mov_b32_e32 v36, v123
	v_mov_b32_e32 v35, v123
	v_mov_b32_e32 v34, v123
	v_mov_b32_e32 v33, v123
	v_mov_b32_e32 v32, v123
	v_mov_b32_e32 v23, v123
	v_mov_b32_e32 v22, v123
	v_mov_b32_e32 v21, v123
	v_mov_b32_e32 v20, v123
	v_mov_b32_e32 v19, v123
	v_mov_b32_e32 v18, v123
	v_mov_b32_e32 v17, v123
	v_mov_b32_e32 v16, v123
	v_mov_b32_e32 v7, v123
	v_mov_b32_e32 v6, v123
	v_mov_b32_e32 v5, v123
	v_mov_b32_e32 v4, v123
	v_mov_b32_e32 v3, v123
	v_mov_b32_e32 v2, v123
	s_waitcnt lgkmcnt(0)
	v_mov_b32_e32 v1, v123
	v_mov_b32_e32 v0, v123
	s_cbranch_vccnz .LBB0_900
	s_add_u32 s52, s52, 0x80
	s_addc_u32 s53, s53, 0
	s_add_u32 s67, s54, 0x100
	v_mov_b32_e32 v0, 0
	s_addc_u32 s68, s55, 0
	s_mov_b32 s54, 0
	v_mov_b32_e32 v1, v0
	v_mov_b32_e32 v2, v0
	v_mov_b32_e32 v3, v0
	v_mov_b32_e32 v4, v0
	v_mov_b32_e32 v5, v0
	v_mov_b32_e32 v6, v0
	v_mov_b32_e32 v7, v0
	v_mov_b32_e32 v16, v0
	v_mov_b32_e32 v17, v0
	v_mov_b32_e32 v18, v0
	v_mov_b32_e32 v19, v0
	v_mov_b32_e32 v20, v0
	v_mov_b32_e32 v21, v0
	v_mov_b32_e32 v22, v0
	v_mov_b32_e32 v23, v0
	v_mov_b32_e32 v32, v0
	v_mov_b32_e32 v33, v0
	v_mov_b32_e32 v34, v0
	v_mov_b32_e32 v35, v0
	v_mov_b32_e32 v36, v0
	v_mov_b32_e32 v37, v0
	v_mov_b32_e32 v38, v0
	v_mov_b32_e32 v39, v0
	v_mov_b32_e32 v48, v0
	v_mov_b32_e32 v49, v0
	v_mov_b32_e32 v50, v0
	v_mov_b32_e32 v51, v0
	v_mov_b32_e32 v52, v0
	v_mov_b32_e32 v53, v0
	v_mov_b32_e32 v54, v0
	v_mov_b32_e32 v55, v0
	v_mov_b32_e32 v8, v0
	v_mov_b32_e32 v9, v0
	v_mov_b32_e32 v10, v0
	v_mov_b32_e32 v11, v0
	v_mov_b32_e32 v12, v0
	v_mov_b32_e32 v13, v0
	v_mov_b32_e32 v14, v0
	v_mov_b32_e32 v15, v0
	v_mov_b32_e32 v24, v0
	v_mov_b32_e32 v25, v0
	v_mov_b32_e32 v26, v0
	v_mov_b32_e32 v27, v0
	v_mov_b32_e32 v28, v0
	v_mov_b32_e32 v29, v0
	v_mov_b32_e32 v30, v0
	v_mov_b32_e32 v31, v0
	v_mov_b32_e32 v40, v0
	v_mov_b32_e32 v41, v0
	v_mov_b32_e32 v42, v0
	v_mov_b32_e32 v43, v0
	v_mov_b32_e32 v44, v0
	v_mov_b32_e32 v45, v0
	v_mov_b32_e32 v46, v0
	v_mov_b32_e32 v47, v0
	v_mov_b32_e32 v56, v0
	v_mov_b32_e32 v57, v0
	v_mov_b32_e32 v58, v0
	v_mov_b32_e32 v59, v0
	v_mov_b32_e32 v60, v0
	v_mov_b32_e32 v61, v0
	v_mov_b32_e32 v62, v0
	v_mov_b32_e32 v63, v0
	v_mov_b32_e32 v64, v0
	v_mov_b32_e32 v65, v0
	v_mov_b32_e32 v66, v0
	v_mov_b32_e32 v67, v0
	v_mov_b32_e32 v68, v0
	v_mov_b32_e32 v69, v0
	v_mov_b32_e32 v70, v0
	v_mov_b32_e32 v71, v0
	v_mov_b32_e32 v80, v0
	v_mov_b32_e32 v81, v0
	v_mov_b32_e32 v82, v0
	v_mov_b32_e32 v83, v0
	v_mov_b32_e32 v84, v0
	v_mov_b32_e32 v85, v0
	v_mov_b32_e32 v86, v0
	v_mov_b32_e32 v87, v0
	v_mov_b32_e32 v96, v0
	v_mov_b32_e32 v97, v0
	v_mov_b32_e32 v98, v0
	v_mov_b32_e32 v99, v0
	v_mov_b32_e32 v100, v0
	v_mov_b32_e32 v101, v0
	v_mov_b32_e32 v102, v0
	v_mov_b32_e32 v103, v0
	v_mov_b32_e32 v112, v0
	v_mov_b32_e32 v113, v0
	v_mov_b32_e32 v114, v0
	v_mov_b32_e32 v115, v0
	v_mov_b32_e32 v116, v0
	v_mov_b32_e32 v117, v0
	v_mov_b32_e32 v118, v0
	v_mov_b32_e32 v119, v0
	v_mov_b32_e32 v72, v0
	v_mov_b32_e32 v73, v0
	v_mov_b32_e32 v74, v0
	v_mov_b32_e32 v75, v0
	v_mov_b32_e32 v76, v0
	v_mov_b32_e32 v77, v0
	v_mov_b32_e32 v78, v0
	v_mov_b32_e32 v79, v0
	v_mov_b32_e32 v88, v0
	v_mov_b32_e32 v89, v0
	v_mov_b32_e32 v90, v0
	v_mov_b32_e32 v91, v0
	v_mov_b32_e32 v92, v0
	v_mov_b32_e32 v93, v0
	v_mov_b32_e32 v94, v0
	v_mov_b32_e32 v95, v0
	v_mov_b32_e32 v104, v0
	v_mov_b32_e32 v105, v0
	v_mov_b32_e32 v106, v0
	v_mov_b32_e32 v107, v0
	v_mov_b32_e32 v108, v0
	v_mov_b32_e32 v109, v0
	v_mov_b32_e32 v110, v0
	v_mov_b32_e32 v111, v0
	v_mov_b32_e32 v124, v0
	v_mov_b32_e32 v125, v0
	v_mov_b32_e32 v126, v0
	v_mov_b32_e32 v127, v0
	v_mov_b32_e32 v120, v0
	v_mov_b32_e32 v121, v0
	v_mov_b32_e32 v122, v0
	v_mov_b32_e32 v123, v0
	.p2align 6
	s_nop 0
	s_nop 0
	s_nop 0
	s_nop 0

; template <class Epi, class Sched, bool ALIGN_EPI = false, bool SP2 = false>
; __device__ __forceinline__ void gemm_phase(PG8_LAS unsigned char* lds, const Gemm g, const Sched& S, const Epi& E, const int wid_in) {
;     ...
;         for (int t = 0; t < nt; t += 2) {
;             const bool last = (t == nt - 2);
;             const char* a1 = cA + (size_t)(t + 1) * kstep;
;             const char* a2 = last ? nA : cA + (size_t)(t + 2) * kstep; const char* b2 = last ? nB : cB + (size_t)(t + 2) * kstep;
;             const char* a3 = a2 + kstep; const char* b3 = b2 + kstep;
;     ...
; #pragma unroll
;         for (int a = 0; a < 2; ++a)
; #pragma unroll
;             for (int b = 0; b < 2; ++b)
; #pragma unroll
;                 for (int m = 0; m < 4; ++m)
; #pragma unroll
;                     for (int n = 0; n < 2; ++n) acc[a][b][m][n] = (f32x4){0.f, 0.f, 0.f, 0.f};
;         cur = nxt; cA = nA; cB = nB; ++ui;
.LBB0_994:
	v_mov_b32_e32 v127, 0
	s_and_b64 vcc, exec, s[10:11]
	v_mov_b32_e32 v126, v127
	v_mov_b32_e32 v125, v127
	v_mov_b32_e32 v124, v127
	v_mov_b32_e32 v123, v127
	v_mov_b32_e32 v122, v127
	v_mov_b32_e32 v121, v127
	v_mov_b32_e32 v120, v127
	v_mov_b32_e32 v111, v127
	v_mov_b32_e32 v110, v127
	v_mov_b32_e32 v109, v127
	v_mov_b32_e32 v108, v127
	v_mov_b32_e32 v107, v127
	v_mov_b32_e32 v106, v127
	v_mov_b32_e32 v105, v127
	v_mov_b32_e32 v104, v127
	v_mov_b32_e32 v95, v127
	v_mov_b32_e32 v94, v127
	v_mov_b32_e32 v93, v127
	v_mov_b32_e32 v92, v127
	v_mov_b32_e32 v91, v127
	v_mov_b32_e32 v90, v127
	v_mov_b32_e32 v89, v127
	v_mov_b32_e32 v88, v127
	v_mov_b32_e32 v79, v127
	v_mov_b32_e32 v78, v127
	v_mov_b32_e32 v77, v127
	v_mov_b32_e32 v76, v127
	v_mov_b32_e32 v75, v127
	v_mov_b32_e32 v74, v127
	v_mov_b32_e32 v73, v127
	v_mov_b32_e32 v72, v127
	v_mov_b32_e32 v115, v127
	v_mov_b32_e32 v114, v127
	v_mov_b32_e32 v113, v127
	v_mov_b32_e32 v112, v127
	v_mov_b32_e32 v119, v127
	v_mov_b32_e32 v118, v127
	v_mov_b32_e32 v117, v127
	v_mov_b32_e32 v116, v127
	v_mov_b32_e32 v99, v127
	v_mov_b32_e32 v98, v127
	v_mov_b32_e32 v97, v127
	v_mov_b32_e32 v96, v127
	v_mov_b32_e32 v103, v127
	v_mov_b32_e32 v102, v127
	v_mov_b32_e32 v101, v127
	v_mov_b32_e32 v100, v127
	v_mov_b32_e32 v83, v127
	v_mov_b32_e32 v82, v127
	v_mov_b32_e32 v81, v127
	v_mov_b32_e32 v80, v127
	v_mov_b32_e32 v87, v127
	v_mov_b32_e32 v86, v127
	v_mov_b32_e32 v85, v127
	v_mov_b32_e32 v84, v127
	v_mov_b32_e32 v67, v127
	v_mov_b32_e32 v66, v127
	v_mov_b32_e32 v65, v127
	v_mov_b32_e32 v64, v127
	v_mov_b32_e32 v71, v127
	v_mov_b32_e32 v70, v127
	v_mov_b32_e32 v69, v127
	v_mov_b32_e32 v68, v127
	v_mov_b32_e32 v63, v127
	v_mov_b32_e32 v62, v127
	v_mov_b32_e32 v61, v127
	v_mov_b32_e32 v60, v127
	v_mov_b32_e32 v59, v127
	v_mov_b32_e32 v58, v127
	v_mov_b32_e32 v57, v127
	v_mov_b32_e32 v56, v127
	v_mov_b32_e32 v47, v127
	v_mov_b32_e32 v46, v127
	v_mov_b32_e32 v45, v127
	v_mov_b32_e32 v44, v127
	v_mov_b32_e32 v43, v127
	v_mov_b32_e32 v42, v127
	v_mov_b32_e32 v41, v127
	v_mov_b32_e32 v40, v127
	v_mov_b32_e32 v31, v127
	v_mov_b32_e32 v30, v127
	v_mov_b32_e32 v29, v127
	v_mov_b32_e32 v28, v127
	v_mov_b32_e32 v27, v127
	v_mov_b32_e32 v26, v127
	v_mov_b32_e32 v25, v127
	v_mov_b32_e32 v24, v127
	v_mov_b32_e32 v15, v127
	v_mov_b32_e32 v14, v127
	v_mov_b32_e32 v13, v127
	v_mov_b32_e32 v12, v127
	v_mov_b32_e32 v11, v127
	v_mov_b32_e32 v10, v127
	v_mov_b32_e32 v9, v127
	v_mov_b32_e32 v8, v127
	v_mov_b32_e32 v51, v127
	v_mov_b32_e32 v50, v127
	v_mov_b32_e32 v49, v127
	v_mov_b32_e32 v48, v127
	v_mov_b32_e32 v55, v127
	v_mov_b32_e32 v54, v127
	v_mov_b32_e32 v53, v127
	v_mov_b32_e32 v52, v127
	v_mov_b32_e32 v35, v127
	v_mov_b32_e32 v34, v127
	v_mov_b32_e32 v33, v127
	v_mov_b32_e32 v32, v127
	v_mov_b32_e32 v39, v127
	v_mov_b32_e32 v38, v127
	v_mov_b32_e32 v37, v127
	v_mov_b32_e32 v36, v127
	v_mov_b32_e32 v19, v127
	v_mov_b32_e32 v18, v127
	v_mov_b32_e32 v17, v127
	v_mov_b32_e32 v16, v127
	v_mov_b32_e32 v23, v127
	v_mov_b32_e32 v22, v127
	v_mov_b32_e32 v21, v127
	v_mov_b32_e32 v20, v127
	v_mov_b32_e32 v3, v127
	v_mov_b32_e32 v2, v127
	v_mov_b32_e32 v1, v127
	v_mov_b32_e32 v0, v127
	v_mov_b32_e32 v7, v127
	v_mov_b32_e32 v6, v127
	v_mov_b32_e32 v5, v127
	v_mov_b32_e32 v4, v127
	s_cbranch_vccnz .LBB0_997
	s_add_u32 s46, s46, 0x80
	s_addc_u32 s47, s47, 0
	s_add_u32 s67, s48, 0x100
	v_mov_b32_e32 v4, 0
	s_addc_u32 s69, s49, 0
	s_mov_b32 s48, 0
	v_mov_b32_e32 v5, v4
	v_mov_b32_e32 v6, v4
	v_mov_b32_e32 v7, v4
	v_mov_b32_e32 v0, v4
	v_mov_b32_e32 v1, v4
	v_mov_b32_e32 v2, v4
	v_mov_b32_e32 v3, v4
	v_mov_b32_e32 v20, v4
	v_mov_b32_e32 v21, v4
	v_mov_b32_e32 v22, v4
	v_mov_b32_e32 v23, v4
	v_mov_b32_e32 v16, v4
	v_mov_b32_e32 v17, v4
	v_mov_b32_e32 v18, v4
	v_mov_b32_e32 v19, v4
	v_mov_b32_e32 v36, v4
	v_mov_b32_e32 v37, v4
	v_mov_b32_e32 v38, v4
	v_mov_b32_e32 v39, v4
	v_mov_b32_e32 v32, v4
	v_mov_b32_e32 v33, v4
	v_mov_b32_e32 v34, v4
	v_mov_b32_e32 v35, v4
	v_mov_b32_e32 v52, v4
	v_mov_b32_e32 v53, v4
	v_mov_b32_e32 v54, v4
	v_mov_b32_e32 v55, v4
	v_mov_b32_e32 v48, v4
	v_mov_b32_e32 v49, v4
	v_mov_b32_e32 v50, v4
	v_mov_b32_e32 v51, v4
	v_mov_b32_e32 v8, v4
	v_mov_b32_e32 v9, v4
	v_mov_b32_e32 v10, v4
	v_mov_b32_e32 v11, v4
	v_mov_b32_e32 v12, v4
	v_mov_b32_e32 v13, v4
	v_mov_b32_e32 v14, v4
	v_mov_b32_e32 v15, v4
	v_mov_b32_e32 v24, v4
	v_mov_b32_e32 v25, v4
	v_mov_b32_e32 v26, v4
	v_mov_b32_e32 v27, v4
	v_mov_b32_e32 v28, v4
	v_mov_b32_e32 v29, v4
	v_mov_b32_e32 v30, v4
	v_mov_b32_e32 v31, v4
	v_mov_b32_e32 v40, v4
	v_mov_b32_e32 v41, v4
	v_mov_b32_e32 v42, v4
	v_mov_b32_e32 v43, v4
	v_mov_b32_e32 v44, v4
	v_mov_b32_e32 v45, v4
	v_mov_b32_e32 v46, v4
	v_mov_b32_e32 v47, v4
	v_mov_b32_e32 v56, v4
	v_mov_b32_e32 v57, v4
	v_mov_b32_e32 v58, v4
	v_mov_b32_e32 v59, v4
	v_mov_b32_e32 v60, v4
	v_mov_b32_e32 v61, v4
	v_mov_b32_e32 v62, v4
	v_mov_b32_e32 v63, v4
	v_mov_b32_e32 v68, v4
	v_mov_b32_e32 v69, v4
	v_mov_b32_e32 v70, v4
	v_mov_b32_e32 v71, v4
	v_mov_b32_e32 v64, v4
	v_mov_b32_e32 v65, v4
	v_mov_b32_e32 v66, v4
	v_mov_b32_e32 v67, v4
	v_mov_b32_e32 v84, v4
	v_mov_b32_e32 v85, v4
	v_mov_b32_e32 v86, v4
	v_mov_b32_e32 v87, v4
	v_mov_b32_e32 v80, v4
	v_mov_b32_e32 v81, v4
	v_mov_b32_e32 v82, v4
	v_mov_b32_e32 v83, v4
	v_mov_b32_e32 v100, v4
	v_mov_b32_e32 v101, v4
	v_mov_b32_e32 v102, v4
	v_mov_b32_e32 v103, v4
	v_mov_b32_e32 v96, v4
	v_mov_b32_e32 v97, v4
	v_mov_b32_e32 v98, v4
	v_mov_b32_e32 v99, v4
	v_mov_b32_e32 v116, v4
	v_mov_b32_e32 v117, v4
	v_mov_b32_e32 v118, v4
	v_mov_b32_e32 v119, v4
	v_mov_b32_e32 v112, v4
	v_mov_b32_e32 v113, v4
	v_mov_b32_e32 v114, v4
	v_mov_b32_e32 v115, v4
	v_mov_b32_e32 v72, v4
	v_mov_b32_e32 v73, v4
	v_mov_b32_e32 v74, v4
	v_mov_b32_e32 v75, v4
	v_mov_b32_e32 v76, v4
	v_mov_b32_e32 v77, v4
	v_mov_b32_e32 v78, v4
	v_mov_b32_e32 v79, v4
	v_mov_b32_e32 v88, v4
	v_mov_b32_e32 v89, v4
	v_mov_b32_e32 v90, v4
	v_mov_b32_e32 v91, v4
	v_mov_b32_e32 v92, v4
	v_mov_b32_e32 v93, v4
	v_mov_b32_e32 v94, v4
	v_mov_b32_e32 v95, v4
	v_mov_b32_e32 v104, v4
	v_mov_b32_e32 v105, v4
	v_mov_b32_e32 v106, v4
	v_mov_b32_e32 v107, v4
	v_mov_b32_e32 v108, v4
	v_mov_b32_e32 v109, v4
	v_mov_b32_e32 v110, v4
	v_mov_b32_e32 v111, v4
	v_mov_b32_e32 v120, v4
	v_mov_b32_e32 v121, v4
	v_mov_b32_e32 v122, v4
	v_mov_b32_e32 v123, v4
	v_mov_b32_e32 v124, v4
	v_mov_b32_e32 v125, v4
	v_mov_b32_e32 v126, v4
	v_mov_b32_e32 v127, v4
	.p2align 6
	s_nop 0
	s_nop 0
	s_nop 0
	s_nop 0
	s_nop 0
	s_nop 0
	s_nop 0
	s_nop 0
	s_nop 0
	s_nop 0
	s_nop 0
	s_nop 0

; template <class Epi, class Sched, bool ALIGN_EPI = false, bool SP2 = false>
; __device__ __forceinline__ void gemm_phase(PG8_LAS unsigned char* lds, const Gemm g, const Sched& S, const Epi& E, const int wid_in) {
;     ...
;         for (int t = 0; t < nt; t += 2) {
;             const bool last = (t == nt - 2);
;             const char* a1 = cA + (size_t)(t + 1) * kstep;
;             const char* a2 = last ? nA : cA + (size_t)(t + 2) * kstep; const char* b2 = last ? nB : cB + (size_t)(t + 2) * kstep;
;             const char* a3 = a2 + kstep; const char* b3 = b2 + kstep;
;     ...
; #pragma unroll
;         for (int a = 0; a < 2; ++a)
; #pragma unroll
;             for (int b = 0; b < 2; ++b)
; #pragma unroll
;                 for (int m = 0; m < 4; ++m)
; #pragma unroll
;                     for (int n = 0; n < 2; ++n) acc[a][b][m][n] = (f32x4){0.f, 0.f, 0.f, 0.f};
;         cur = nxt; cA = nA; cB = nB; ++ui;
.LBB0_1016:
	v_mov_b32_e32 v123, 0
	s_and_b64 vcc, exec, s[10:11]
	v_mov_b32_e32 v122, v123
	v_mov_b32_e32 v121, v123
	v_mov_b32_e32 v120, v123
	v_mov_b32_e32 v127, v123
	v_mov_b32_e32 v126, v123
	v_mov_b32_e32 v125, v123
	v_mov_b32_e32 v124, v123
	v_mov_b32_e32 v107, v123
	v_mov_b32_e32 v106, v123
	v_mov_b32_e32 v105, v123
	v_mov_b32_e32 v104, v123
	v_mov_b32_e32 v111, v123
	v_mov_b32_e32 v110, v123
	v_mov_b32_e32 v109, v123
	v_mov_b32_e32 v108, v123
	v_mov_b32_e32 v91, v123
	v_mov_b32_e32 v90, v123
	v_mov_b32_e32 v89, v123
	v_mov_b32_e32 v88, v123
	v_mov_b32_e32 v95, v123
	v_mov_b32_e32 v94, v123
	v_mov_b32_e32 v93, v123
	v_mov_b32_e32 v92, v123
	v_mov_b32_e32 v75, v123
	v_mov_b32_e32 v74, v123
	v_mov_b32_e32 v73, v123
	v_mov_b32_e32 v72, v123
	v_mov_b32_e32 v79, v123
	v_mov_b32_e32 v78, v123
	v_mov_b32_e32 v77, v123
	v_mov_b32_e32 v76, v123
	v_mov_b32_e32 v115, v123
	v_mov_b32_e32 v114, v123
	v_mov_b32_e32 v113, v123
	v_mov_b32_e32 v112, v123
	v_mov_b32_e32 v119, v123
	v_mov_b32_e32 v118, v123
	v_mov_b32_e32 v117, v123
	v_mov_b32_e32 v116, v123
	v_mov_b32_e32 v99, v123
	v_mov_b32_e32 v98, v123
	v_mov_b32_e32 v97, v123
	v_mov_b32_e32 v96, v123
	v_mov_b32_e32 v103, v123
	v_mov_b32_e32 v102, v123
	v_mov_b32_e32 v101, v123
	v_mov_b32_e32 v100, v123
	v_mov_b32_e32 v83, v123
	v_mov_b32_e32 v82, v123
	v_mov_b32_e32 v81, v123
	v_mov_b32_e32 v80, v123
	v_mov_b32_e32 v87, v123
	v_mov_b32_e32 v86, v123
	v_mov_b32_e32 v85, v123
	v_mov_b32_e32 v84, v123
	v_mov_b32_e32 v67, v123
	v_mov_b32_e32 v66, v123
	v_mov_b32_e32 v65, v123
	v_mov_b32_e32 v64, v123
	v_mov_b32_e32 v71, v123
	v_mov_b32_e32 v70, v123
	v_mov_b32_e32 v69, v123
	v_mov_b32_e32 v68, v123
	v_mov_b32_e32 v59, v123
	v_mov_b32_e32 v58, v123
	v_mov_b32_e32 v57, v123
	v_mov_b32_e32 v56, v123
	v_mov_b32_e32 v63, v123
	v_mov_b32_e32 v62, v123
	v_mov_b32_e32 v61, v123
	v_mov_b32_e32 v60, v123
	v_mov_b32_e32 v43, v123
	v_mov_b32_e32 v42, v123
	v_mov_b32_e32 v41, v123
	v_mov_b32_e32 v40, v123
	v_mov_b32_e32 v47, v123
	v_mov_b32_e32 v46, v123
	v_mov_b32_e32 v45, v123
	v_mov_b32_e32 v44, v123
	v_mov_b32_e32 v27, v123
	v_mov_b32_e32 v26, v123
	v_mov_b32_e32 v25, v123
	v_mov_b32_e32 v24, v123
	v_mov_b32_e32 v31, v123
	v_mov_b32_e32 v30, v123
	v_mov_b32_e32 v29, v123
	v_mov_b32_e32 v28, v123
	v_mov_b32_e32 v11, v123
	v_mov_b32_e32 v10, v123
	v_mov_b32_e32 v9, v123
	v_mov_b32_e32 v8, v123
	v_mov_b32_e32 v15, v123
	v_mov_b32_e32 v14, v123
	v_mov_b32_e32 v13, v123
	v_mov_b32_e32 v12, v123
	v_mov_b32_e32 v51, v123
	v_mov_b32_e32 v50, v123
	v_mov_b32_e32 v49, v123
	v_mov_b32_e32 v48, v123
	v_mov_b32_e32 v55, v123
	v_mov_b32_e32 v54, v123
	v_mov_b32_e32 v53, v123
	v_mov_b32_e32 v52, v123
	v_mov_b32_e32 v35, v123
	v_mov_b32_e32 v34, v123
	v_mov_b32_e32 v33, v123
	v_mov_b32_e32 v32, v123
	v_mov_b32_e32 v39, v123
	v_mov_b32_e32 v38, v123
	v_mov_b32_e32 v37, v123
	v_mov_b32_e32 v36, v123
	v_mov_b32_e32 v19, v123
	v_mov_b32_e32 v18, v123
	v_mov_b32_e32 v17, v123
	v_mov_b32_e32 v16, v123
	v_mov_b32_e32 v23, v123
	v_mov_b32_e32 v22, v123
	v_mov_b32_e32 v21, v123
	v_mov_b32_e32 v20, v123
	v_mov_b32_e32 v7, v123
	v_mov_b32_e32 v6, v123
	v_mov_b32_e32 v5, v123
	v_mov_b32_e32 v4, v123
	v_mov_b32_e32 v3, v123
	v_mov_b32_e32 v2, v123
	v_mov_b32_e32 v1, v123
	v_mov_b32_e32 v0, v123
	s_cbranch_vccnz .LBB0_1019
	s_add_u32 s50, s50, 0x80
	s_addc_u32 s51, s51, 0
	s_add_u32 s84, s52, 0x100
	v_mov_b32_e32 v0, 0
	s_addc_u32 s87, s53, 0
	s_mov_b32 s52, 0
	v_mov_b32_e32 v1, v0
	v_mov_b32_e32 v2, v0
	v_mov_b32_e32 v3, v0
	v_mov_b32_e32 v4, v0
	v_mov_b32_e32 v5, v0
	v_mov_b32_e32 v6, v0
	v_mov_b32_e32 v7, v0
	v_mov_b32_e32 v20, v0
	v_mov_b32_e32 v21, v0
	v_mov_b32_e32 v22, v0
	v_mov_b32_e32 v23, v0
	v_mov_b32_e32 v16, v0
	v_mov_b32_e32 v17, v0
	v_mov_b32_e32 v18, v0
	v_mov_b32_e32 v19, v0
	v_mov_b32_e32 v36, v0
	v_mov_b32_e32 v37, v0
	v_mov_b32_e32 v38, v0
	v_mov_b32_e32 v39, v0
	v_mov_b32_e32 v32, v0
	v_mov_b32_e32 v33, v0
	v_mov_b32_e32 v34, v0
	v_mov_b32_e32 v35, v0
	v_mov_b32_e32 v52, v0
	v_mov_b32_e32 v53, v0
	v_mov_b32_e32 v54, v0
	v_mov_b32_e32 v55, v0
	v_mov_b32_e32 v48, v0
	v_mov_b32_e32 v49, v0
	v_mov_b32_e32 v50, v0
	v_mov_b32_e32 v51, v0
	v_mov_b32_e32 v12, v0
	v_mov_b32_e32 v13, v0
	v_mov_b32_e32 v14, v0
	v_mov_b32_e32 v15, v0
	v_mov_b32_e32 v8, v0
	v_mov_b32_e32 v9, v0
	v_mov_b32_e32 v10, v0
	v_mov_b32_e32 v11, v0
	v_mov_b32_e32 v28, v0
	v_mov_b32_e32 v29, v0
	v_mov_b32_e32 v30, v0
	v_mov_b32_e32 v31, v0
	v_mov_b32_e32 v24, v0
	v_mov_b32_e32 v25, v0
	v_mov_b32_e32 v26, v0
	v_mov_b32_e32 v27, v0
	v_mov_b32_e32 v44, v0
	v_mov_b32_e32 v45, v0
	v_mov_b32_e32 v46, v0
	v_mov_b32_e32 v47, v0
	v_mov_b32_e32 v40, v0
	v_mov_b32_e32 v41, v0
	v_mov_b32_e32 v42, v0
	v_mov_b32_e32 v43, v0
	v_mov_b32_e32 v60, v0
	v_mov_b32_e32 v61, v0
	v_mov_b32_e32 v62, v0
	v_mov_b32_e32 v63, v0
	v_mov_b32_e32 v56, v0
	v_mov_b32_e32 v57, v0
	v_mov_b32_e32 v58, v0
	v_mov_b32_e32 v59, v0
	v_mov_b32_e32 v68, v0
	v_mov_b32_e32 v69, v0
	v_mov_b32_e32 v70, v0
	v_mov_b32_e32 v71, v0
	v_mov_b32_e32 v64, v0
	v_mov_b32_e32 v65, v0
	v_mov_b32_e32 v66, v0
	v_mov_b32_e32 v67, v0
	v_mov_b32_e32 v84, v0
	v_mov_b32_e32 v85, v0
	v_mov_b32_e32 v86, v0
	v_mov_b32_e32 v87, v0
	v_mov_b32_e32 v80, v0
	v_mov_b32_e32 v81, v0
	v_mov_b32_e32 v82, v0
	v_mov_b32_e32 v83, v0
	v_mov_b32_e32 v100, v0
	v_mov_b32_e32 v101, v0
	v_mov_b32_e32 v102, v0
	v_mov_b32_e32 v103, v0
	v_mov_b32_e32 v96, v0
	v_mov_b32_e32 v97, v0
	v_mov_b32_e32 v98, v0
	v_mov_b32_e32 v99, v0
	v_mov_b32_e32 v116, v0
	v_mov_b32_e32 v117, v0
	v_mov_b32_e32 v118, v0
	v_mov_b32_e32 v119, v0
	v_mov_b32_e32 v112, v0
	v_mov_b32_e32 v113, v0
	v_mov_b32_e32 v114, v0
	v_mov_b32_e32 v115, v0
	v_mov_b32_e32 v76, v0
	v_mov_b32_e32 v77, v0
	v_mov_b32_e32 v78, v0
	v_mov_b32_e32 v79, v0
	v_mov_b32_e32 v72, v0
	v_mov_b32_e32 v73, v0
	v_mov_b32_e32 v74, v0
	v_mov_b32_e32 v75, v0
	v_mov_b32_e32 v92, v0
	v_mov_b32_e32 v93, v0
	v_mov_b32_e32 v94, v0
	v_mov_b32_e32 v95, v0
	v_mov_b32_e32 v88, v0
	v_mov_b32_e32 v89, v0
	v_mov_b32_e32 v90, v0
	v_mov_b32_e32 v91, v0
	v_mov_b32_e32 v108, v0
	v_mov_b32_e32 v109, v0
	v_mov_b32_e32 v110, v0
	v_mov_b32_e32 v111, v0
	v_mov_b32_e32 v104, v0
	v_mov_b32_e32 v105, v0
	v_mov_b32_e32 v106, v0
	v_mov_b32_e32 v107, v0
	v_mov_b32_e32 v124, v0
	v_mov_b32_e32 v125, v0
	v_mov_b32_e32 v126, v0
	v_mov_b32_e32 v127, v0
	v_mov_b32_e32 v120, v0
	v_mov_b32_e32 v121, v0
	v_mov_b32_e32 v122, v0
	v_mov_b32_e32 v123, v0
	.p2align 6
	s_nop 0
	s_nop 0
	s_nop 0
	s_nop 0
	s_nop 0
	s_nop 0
	s_nop 0
	s_nop 0
	s_nop 0
	s_nop 0
	s_nop 0
	s_nop 0
	s_nop 0
	s_nop 0
	s_nop 0

; template <class Epi, class Sched, bool ALIGN_EPI = false, bool SP2 = false>
; __device__ __forceinline__ void gemm_phase(PG8_LAS unsigned char* lds, const Gemm g, const Sched& S, const Epi& E, const int wid_in) {
;     ...
;         for (int t = 0; t < nt; t += 2) {
;             const bool last = (t == nt - 2);
;             const char* a1 = cA + (size_t)(t + 1) * kstep;
;             const char* a2 = last ? nA : cA + (size_t)(t + 2) * kstep; const char* b2 = last ? nB : cB + (size_t)(t + 2) * kstep;
;             const char* a3 = a2 + kstep; const char* b3 = b2 + kstep;
;     ...
; #pragma unroll
;         for (int a = 0; a < 2; ++a)
; #pragma unroll
;             for (int b = 0; b < 2; ++b)
; #pragma unroll
;                 for (int m = 0; m < 4; ++m)
; #pragma unroll
;                     for (int n = 0; n < 2; ++n) acc[a][b][m][n] = (f32x4){0.f, 0.f, 0.f, 0.f};
;         cur = nxt; cA = nA; cB = nB; ++ui;
.LBB0_1099:
	v_mov_b32_e32 v127, 0
	s_and_b64 vcc, exec, s[12:13]
	v_mov_b32_e32 v126, v127
	v_mov_b32_e32 v125, v127
	v_mov_b32_e32 v124, v127
	v_mov_b32_e32 v123, v127
	v_mov_b32_e32 v122, v127
	v_mov_b32_e32 v121, v127
	v_mov_b32_e32 v120, v127
	v_mov_b32_e32 v111, v127
	v_mov_b32_e32 v110, v127
	v_mov_b32_e32 v109, v127
	v_mov_b32_e32 v108, v127
	v_mov_b32_e32 v107, v127
	v_mov_b32_e32 v106, v127
	v_mov_b32_e32 v105, v127
	v_mov_b32_e32 v104, v127
	v_mov_b32_e32 v95, v127
	v_mov_b32_e32 v94, v127
	v_mov_b32_e32 v93, v127
	v_mov_b32_e32 v92, v127
	v_mov_b32_e32 v91, v127
	v_mov_b32_e32 v90, v127
	v_mov_b32_e32 v89, v127
	v_mov_b32_e32 v88, v127
	v_mov_b32_e32 v79, v127
	v_mov_b32_e32 v78, v127
	v_mov_b32_e32 v77, v127
	v_mov_b32_e32 v76, v127
	v_mov_b32_e32 v75, v127
	v_mov_b32_e32 v74, v127
	v_mov_b32_e32 v73, v127
	v_mov_b32_e32 v72, v127
	v_mov_b32_e32 v119, v127
	v_mov_b32_e32 v118, v127
	v_mov_b32_e32 v117, v127
	v_mov_b32_e32 v116, v127
	v_mov_b32_e32 v115, v127
	v_mov_b32_e32 v114, v127
	v_mov_b32_e32 v113, v127
	v_mov_b32_e32 v112, v127
	v_mov_b32_e32 v103, v127
	v_mov_b32_e32 v102, v127
	v_mov_b32_e32 v101, v127
	v_mov_b32_e32 v100, v127
	v_mov_b32_e32 v99, v127
	v_mov_b32_e32 v98, v127
	v_mov_b32_e32 v97, v127
	v_mov_b32_e32 v96, v127
	v_mov_b32_e32 v87, v127
	v_mov_b32_e32 v86, v127
	v_mov_b32_e32 v85, v127
	v_mov_b32_e32 v84, v127
	v_mov_b32_e32 v83, v127
	v_mov_b32_e32 v82, v127
	v_mov_b32_e32 v81, v127
	v_mov_b32_e32 v80, v127
	v_mov_b32_e32 v71, v127
	v_mov_b32_e32 v70, v127
	v_mov_b32_e32 v69, v127
	v_mov_b32_e32 v68, v127
	v_mov_b32_e32 v67, v127
	v_mov_b32_e32 v66, v127
	v_mov_b32_e32 v65, v127
	v_mov_b32_e32 v64, v127
	v_mov_b32_e32 v63, v127
	v_mov_b32_e32 v62, v127
	v_mov_b32_e32 v61, v127
	v_mov_b32_e32 v60, v127
	v_mov_b32_e32 v59, v127
	v_mov_b32_e32 v58, v127
	v_mov_b32_e32 v57, v127
	v_mov_b32_e32 v56, v127
	v_mov_b32_e32 v47, v127
	v_mov_b32_e32 v46, v127
	v_mov_b32_e32 v45, v127
	v_mov_b32_e32 v44, v127
	v_mov_b32_e32 v43, v127
	v_mov_b32_e32 v42, v127
	v_mov_b32_e32 v41, v127
	v_mov_b32_e32 v40, v127
	v_mov_b32_e32 v31, v127
	v_mov_b32_e32 v30, v127
	v_mov_b32_e32 v29, v127
	v_mov_b32_e32 v28, v127
	v_mov_b32_e32 v27, v127
	v_mov_b32_e32 v26, v127
	v_mov_b32_e32 v25, v127
	v_mov_b32_e32 v24, v127
	v_mov_b32_e32 v15, v127
	v_mov_b32_e32 v14, v127
	v_mov_b32_e32 v13, v127
	v_mov_b32_e32 v12, v127
	v_mov_b32_e32 v11, v127
	v_mov_b32_e32 v10, v127
	v_mov_b32_e32 v9, v127
	v_mov_b32_e32 v8, v127
	v_mov_b32_e32 v55, v127
	v_mov_b32_e32 v54, v127
	v_mov_b32_e32 v53, v127
	v_mov_b32_e32 v52, v127
	v_mov_b32_e32 v51, v127
	v_mov_b32_e32 v50, v127
	v_mov_b32_e32 v49, v127
	v_mov_b32_e32 v48, v127
	v_mov_b32_e32 v39, v127
	v_mov_b32_e32 v38, v127
	v_mov_b32_e32 v37, v127
	v_mov_b32_e32 v36, v127
	v_mov_b32_e32 v35, v127
	v_mov_b32_e32 v34, v127
	v_mov_b32_e32 v33, v127
	v_mov_b32_e32 v32, v127
	v_mov_b32_e32 v23, v127
	v_mov_b32_e32 v22, v127
	v_mov_b32_e32 v21, v127
	v_mov_b32_e32 v20, v127
	v_mov_b32_e32 v19, v127
	v_mov_b32_e32 v18, v127
	v_mov_b32_e32 v17, v127
	v_mov_b32_e32 v16, v127
	v_mov_b32_e32 v7, v127
	v_mov_b32_e32 v6, v127
	v_mov_b32_e32 v5, v127
	v_mov_b32_e32 v4, v127
	v_mov_b32_e32 v3, v127
	v_mov_b32_e32 v2, v127
	s_waitcnt lgkmcnt(0)
	v_mov_b32_e32 v1, v127
	v_mov_b32_e32 v0, v127
	s_cbranch_vccnz .LBB0_1102
	s_add_u32 s50, s50, 0x80
	s_addc_u32 s51, s51, 0
	s_add_u32 s66, s52, 0x100
	v_mov_b32_e32 v0, 0
	s_addc_u32 s67, s53, 0
	s_mov_b32 s52, 0
	v_mov_b32_e32 v1, v0
	v_mov_b32_e32 v2, v0
	v_mov_b32_e32 v3, v0
	v_mov_b32_e32 v4, v0
	v_mov_b32_e32 v5, v0
	v_mov_b32_e32 v6, v0
	v_mov_b32_e32 v7, v0
	v_mov_b32_e32 v16, v0
	v_mov_b32_e32 v17, v0
	v_mov_b32_e32 v18, v0
	v_mov_b32_e32 v19, v0
	v_mov_b32_e32 v20, v0
	v_mov_b32_e32 v21, v0
	v_mov_b32_e32 v22, v0
	v_mov_b32_e32 v23, v0
	v_mov_b32_e32 v32, v0
	v_mov_b32_e32 v33, v0
	v_mov_b32_e32 v34, v0
	v_mov_b32_e32 v35, v0
	v_mov_b32_e32 v36, v0
	v_mov_b32_e32 v37, v0
	v_mov_b32_e32 v38, v0
	v_mov_b32_e32 v39, v0
	v_mov_b32_e32 v48, v0
	v_mov_b32_e32 v49, v0
	v_mov_b32_e32 v50, v0
	v_mov_b32_e32 v51, v0
	v_mov_b32_e32 v52, v0
	v_mov_b32_e32 v53, v0
	v_mov_b32_e32 v54, v0
	v_mov_b32_e32 v55, v0
	v_mov_b32_e32 v8, v0
	v_mov_b32_e32 v9, v0
	v_mov_b32_e32 v10, v0
	v_mov_b32_e32 v11, v0
	v_mov_b32_e32 v12, v0
	v_mov_b32_e32 v13, v0
	v_mov_b32_e32 v14, v0
	v_mov_b32_e32 v15, v0
	v_mov_b32_e32 v24, v0
	v_mov_b32_e32 v25, v0
	v_mov_b32_e32 v26, v0
	v_mov_b32_e32 v27, v0
	v_mov_b32_e32 v28, v0
	v_mov_b32_e32 v29, v0
	v_mov_b32_e32 v30, v0
	v_mov_b32_e32 v31, v0
	v_mov_b32_e32 v40, v0
	v_mov_b32_e32 v41, v0
	v_mov_b32_e32 v42, v0
	v_mov_b32_e32 v43, v0
	v_mov_b32_e32 v44, v0
	v_mov_b32_e32 v45, v0
	v_mov_b32_e32 v46, v0
	v_mov_b32_e32 v47, v0
	v_mov_b32_e32 v56, v0
	v_mov_b32_e32 v57, v0
	v_mov_b32_e32 v58, v0
	v_mov_b32_e32 v59, v0
	v_mov_b32_e32 v60, v0
	v_mov_b32_e32 v61, v0
	v_mov_b32_e32 v62, v0
	v_mov_b32_e32 v63, v0
	v_mov_b32_e32 v64, v0
	v_mov_b32_e32 v65, v0
	v_mov_b32_e32 v66, v0
	v_mov_b32_e32 v67, v0
	v_mov_b32_e32 v68, v0
	v_mov_b32_e32 v69, v0
	v_mov_b32_e32 v70, v0
	v_mov_b32_e32 v71, v0
	v_mov_b32_e32 v80, v0
	v_mov_b32_e32 v81, v0
	v_mov_b32_e32 v82, v0
	v_mov_b32_e32 v83, v0
	v_mov_b32_e32 v84, v0
	v_mov_b32_e32 v85, v0
	v_mov_b32_e32 v86, v0
	v_mov_b32_e32 v87, v0
	v_mov_b32_e32 v96, v0
	v_mov_b32_e32 v97, v0
	v_mov_b32_e32 v98, v0
	v_mov_b32_e32 v99, v0
	v_mov_b32_e32 v100, v0
	v_mov_b32_e32 v101, v0
	v_mov_b32_e32 v102, v0
	v_mov_b32_e32 v103, v0
	v_mov_b32_e32 v112, v0
	v_mov_b32_e32 v113, v0
	v_mov_b32_e32 v114, v0
	v_mov_b32_e32 v115, v0
	v_mov_b32_e32 v116, v0
	v_mov_b32_e32 v117, v0
	v_mov_b32_e32 v118, v0
	v_mov_b32_e32 v119, v0
	v_mov_b32_e32 v72, v0
	v_mov_b32_e32 v73, v0
	v_mov_b32_e32 v74, v0
	v_mov_b32_e32 v75, v0
	v_mov_b32_e32 v76, v0
	v_mov_b32_e32 v77, v0
	v_mov_b32_e32 v78, v0
	v_mov_b32_e32 v79, v0
	v_mov_b32_e32 v88, v0
	v_mov_b32_e32 v89, v0
	v_mov_b32_e32 v90, v0
	v_mov_b32_e32 v91, v0
	v_mov_b32_e32 v92, v0
	v_mov_b32_e32 v93, v0
	v_mov_b32_e32 v94, v0
	v_mov_b32_e32 v95, v0
	v_mov_b32_e32 v104, v0
	v_mov_b32_e32 v105, v0
	v_mov_b32_e32 v106, v0
	v_mov_b32_e32 v107, v0
	v_mov_b32_e32 v108, v0
	v_mov_b32_e32 v109, v0
	v_mov_b32_e32 v110, v0
	v_mov_b32_e32 v111, v0
	v_mov_b32_e32 v120, v0
	v_mov_b32_e32 v121, v0
	v_mov_b32_e32 v122, v0
	v_mov_b32_e32 v123, v0
	v_mov_b32_e32 v124, v0
	v_mov_b32_e32 v125, v0
	v_mov_b32_e32 v126, v0
	v_mov_b32_e32 v127, v0
	.p2align 6
	s_nop 0
	s_nop 0

; template <class Epi, class Sched, bool ALIGN_EPI = false, bool SP2 = false>
; __device__ __forceinline__ void gemm_phase(PG8_LAS unsigned char* lds, const Gemm g, const Sched& S, const Epi& E, const int wid_in) {
;     ...
;         for (int t = 0; t < nt; t += 2) {
;             const bool last = (t == nt - 2);
;             const char* a1 = cA + (size_t)(t + 1) * kstep;
;             const char* a2 = last ? nA : cA + (size_t)(t + 2) * kstep; const char* b2 = last ? nB : cB + (size_t)(t + 2) * kstep;
;             const char* a3 = a2 + kstep; const char* b3 = b2 + kstep;
;     ...
; #pragma unroll
;         for (int a = 0; a < 2; ++a)
; #pragma unroll
;             for (int b = 0; b < 2; ++b)
; #pragma unroll
;                 for (int m = 0; m < 4; ++m)
; #pragma unroll
;                     for (int n = 0; n < 2; ++n) acc[a][b][m][n] = (f32x4){0.f, 0.f, 0.f, 0.f};
;         cur = nxt; cA = nA; cB = nB; ++ui;
.LBB0_1197:
	v_mov_b32_e32 v123, 0
	s_andn2_b64 vcc, exec, s[20:21]
	v_mov_b32_e32 v122, v123
	v_mov_b32_e32 v121, v123
	v_mov_b32_e32 v120, v123
	v_mov_b32_e32 v127, v123
	v_mov_b32_e32 v126, v123
	v_mov_b32_e32 v125, v123
	v_mov_b32_e32 v124, v123
	v_mov_b32_e32 v107, v123
	v_mov_b32_e32 v106, v123
	v_mov_b32_e32 v105, v123
	v_mov_b32_e32 v104, v123
	v_mov_b32_e32 v111, v123
	v_mov_b32_e32 v110, v123
	v_mov_b32_e32 v109, v123
	v_mov_b32_e32 v108, v123
	v_mov_b32_e32 v91, v123
	v_mov_b32_e32 v90, v123
	v_mov_b32_e32 v89, v123
	v_mov_b32_e32 v88, v123
	v_mov_b32_e32 v95, v123
	v_mov_b32_e32 v94, v123
	v_mov_b32_e32 v93, v123
	v_mov_b32_e32 v92, v123
	v_mov_b32_e32 v75, v123
	v_mov_b32_e32 v74, v123
	v_mov_b32_e32 v73, v123
	v_mov_b32_e32 v72, v123
	v_mov_b32_e32 v79, v123
	v_mov_b32_e32 v78, v123
	v_mov_b32_e32 v77, v123
	v_mov_b32_e32 v76, v123
	v_mov_b32_e32 v115, v123
	v_mov_b32_e32 v114, v123
	v_mov_b32_e32 v113, v123
	v_mov_b32_e32 v112, v123
	v_mov_b32_e32 v119, v123
	v_mov_b32_e32 v118, v123
	v_mov_b32_e32 v117, v123
	v_mov_b32_e32 v116, v123
	v_mov_b32_e32 v99, v123
	v_mov_b32_e32 v98, v123
	v_mov_b32_e32 v97, v123
	v_mov_b32_e32 v96, v123
	v_mov_b32_e32 v103, v123
	v_mov_b32_e32 v102, v123
	v_mov_b32_e32 v101, v123
	v_mov_b32_e32 v100, v123
	v_mov_b32_e32 v83, v123
	v_mov_b32_e32 v82, v123
	v_mov_b32_e32 v81, v123
	v_mov_b32_e32 v80, v123
	v_mov_b32_e32 v87, v123
	v_mov_b32_e32 v86, v123
	v_mov_b32_e32 v85, v123
	v_mov_b32_e32 v84, v123
	v_mov_b32_e32 v67, v123
	v_mov_b32_e32 v66, v123
	v_mov_b32_e32 v65, v123
	v_mov_b32_e32 v64, v123
	v_mov_b32_e32 v71, v123
	v_mov_b32_e32 v70, v123
	v_mov_b32_e32 v69, v123
	v_mov_b32_e32 v68, v123
	v_mov_b32_e32 v59, v123
	v_mov_b32_e32 v58, v123
	v_mov_b32_e32 v57, v123
	v_mov_b32_e32 v56, v123
	v_mov_b32_e32 v63, v123
	v_mov_b32_e32 v62, v123
	v_mov_b32_e32 v61, v123
	v_mov_b32_e32 v60, v123
	v_mov_b32_e32 v43, v123
	v_mov_b32_e32 v42, v123
	v_mov_b32_e32 v41, v123
	v_mov_b32_e32 v40, v123
	v_mov_b32_e32 v47, v123
	v_mov_b32_e32 v46, v123
	v_mov_b32_e32 v45, v123
	v_mov_b32_e32 v44, v123
	v_mov_b32_e32 v27, v123
	v_mov_b32_e32 v26, v123
	v_mov_b32_e32 v25, v123
	v_mov_b32_e32 v24, v123
	v_mov_b32_e32 v31, v123
	v_mov_b32_e32 v30, v123
	v_mov_b32_e32 v29, v123
	v_mov_b32_e32 v28, v123
	v_mov_b32_e32 v11, v123
	v_mov_b32_e32 v10, v123
	v_mov_b32_e32 v9, v123
	v_mov_b32_e32 v8, v123
	v_mov_b32_e32 v15, v123
	v_mov_b32_e32 v14, v123
	v_mov_b32_e32 v13, v123
	v_mov_b32_e32 v12, v123
	v_mov_b32_e32 v51, v123
	v_mov_b32_e32 v50, v123
	v_mov_b32_e32 v49, v123
	v_mov_b32_e32 v48, v123
	v_mov_b32_e32 v55, v123
	v_mov_b32_e32 v54, v123
	v_mov_b32_e32 v53, v123
	v_mov_b32_e32 v52, v123
	v_mov_b32_e32 v35, v123
	v_mov_b32_e32 v34, v123
	v_mov_b32_e32 v33, v123
	v_mov_b32_e32 v32, v123
	v_mov_b32_e32 v39, v123
	v_mov_b32_e32 v38, v123
	v_mov_b32_e32 v37, v123
	v_mov_b32_e32 v36, v123
	v_mov_b32_e32 v19, v123
	v_mov_b32_e32 v18, v123
	v_mov_b32_e32 v17, v123
	v_mov_b32_e32 v16, v123
	v_mov_b32_e32 v23, v123
	v_mov_b32_e32 v22, v123
	v_mov_b32_e32 v21, v123
	v_mov_b32_e32 v20, v123
	v_mov_b32_e32 v7, v123
	v_mov_b32_e32 v6, v123
	v_mov_b32_e32 v5, v123
	v_mov_b32_e32 v4, v123
	v_mov_b32_e32 v3, v123
	v_mov_b32_e32 v2, v123
	v_mov_b32_e32 v1, v123
	v_mov_b32_e32 v0, v123
	s_cbranch_vccnz .LBB0_1200
	s_add_u32 s42, s42, 0x80
	s_addc_u32 s43, s43, 0
	s_add_u32 s67, s44, 0x100
	v_mov_b32_e32 v0, 0
	s_addc_u32 s69, s45, 0
	s_mov_b32 s44, 0
	v_mov_b32_e32 v1, v0
	v_mov_b32_e32 v2, v0
	v_mov_b32_e32 v3, v0
	v_mov_b32_e32 v4, v0
	v_mov_b32_e32 v5, v0
	v_mov_b32_e32 v6, v0
	v_mov_b32_e32 v7, v0
	v_mov_b32_e32 v20, v0
	v_mov_b32_e32 v21, v0
	v_mov_b32_e32 v22, v0
	v_mov_b32_e32 v23, v0
	v_mov_b32_e32 v16, v0
	v_mov_b32_e32 v17, v0
	v_mov_b32_e32 v18, v0
	v_mov_b32_e32 v19, v0
	v_mov_b32_e32 v36, v0
	v_mov_b32_e32 v37, v0
	v_mov_b32_e32 v38, v0
	v_mov_b32_e32 v39, v0
	v_mov_b32_e32 v32, v0
	v_mov_b32_e32 v33, v0
	v_mov_b32_e32 v34, v0
	v_mov_b32_e32 v35, v0
	v_mov_b32_e32 v52, v0
	v_mov_b32_e32 v53, v0
	v_mov_b32_e32 v54, v0
	v_mov_b32_e32 v55, v0
	v_mov_b32_e32 v48, v0
	v_mov_b32_e32 v49, v0
	v_mov_b32_e32 v50, v0
	v_mov_b32_e32 v51, v0
	v_mov_b32_e32 v12, v0
	v_mov_b32_e32 v13, v0
	v_mov_b32_e32 v14, v0
	v_mov_b32_e32 v15, v0
	v_mov_b32_e32 v8, v0
	v_mov_b32_e32 v9, v0
	v_mov_b32_e32 v10, v0
	v_mov_b32_e32 v11, v0
	v_mov_b32_e32 v28, v0
	v_mov_b32_e32 v29, v0
	v_mov_b32_e32 v30, v0
	v_mov_b32_e32 v31, v0
	v_mov_b32_e32 v24, v0
	v_mov_b32_e32 v25, v0
	v_mov_b32_e32 v26, v0
	v_mov_b32_e32 v27, v0
	v_mov_b32_e32 v44, v0
	v_mov_b32_e32 v45, v0
	v_mov_b32_e32 v46, v0
	v_mov_b32_e32 v47, v0
	v_mov_b32_e32 v40, v0
	v_mov_b32_e32 v41, v0
	v_mov_b32_e32 v42, v0
	v_mov_b32_e32 v43, v0
	v_mov_b32_e32 v60, v0
	v_mov_b32_e32 v61, v0
	v_mov_b32_e32 v62, v0
	v_mov_b32_e32 v63, v0
	v_mov_b32_e32 v56, v0
	v_mov_b32_e32 v57, v0
	v_mov_b32_e32 v58, v0
	v_mov_b32_e32 v59, v0
	v_mov_b32_e32 v68, v0
	v_mov_b32_e32 v69, v0
	v_mov_b32_e32 v70, v0
	v_mov_b32_e32 v71, v0
	v_mov_b32_e32 v64, v0
	v_mov_b32_e32 v65, v0
	v_mov_b32_e32 v66, v0
	v_mov_b32_e32 v67, v0
	v_mov_b32_e32 v84, v0
	v_mov_b32_e32 v85, v0
	v_mov_b32_e32 v86, v0
	v_mov_b32_e32 v87, v0
	v_mov_b32_e32 v80, v0
	v_mov_b32_e32 v81, v0
	v_mov_b32_e32 v82, v0
	v_mov_b32_e32 v83, v0
	v_mov_b32_e32 v100, v0
	v_mov_b32_e32 v101, v0
	v_mov_b32_e32 v102, v0
	v_mov_b32_e32 v103, v0
	v_mov_b32_e32 v96, v0
	v_mov_b32_e32 v97, v0
	v_mov_b32_e32 v98, v0
	v_mov_b32_e32 v99, v0
	v_mov_b32_e32 v116, v0
	v_mov_b32_e32 v117, v0
	v_mov_b32_e32 v118, v0
	v_mov_b32_e32 v119, v0
	v_mov_b32_e32 v112, v0
	v_mov_b32_e32 v113, v0
	v_mov_b32_e32 v114, v0
	v_mov_b32_e32 v115, v0
	v_mov_b32_e32 v76, v0
	v_mov_b32_e32 v77, v0
	v_mov_b32_e32 v78, v0
	v_mov_b32_e32 v79, v0
	v_mov_b32_e32 v72, v0
	v_mov_b32_e32 v73, v0
	v_mov_b32_e32 v74, v0
	v_mov_b32_e32 v75, v0
	v_mov_b32_e32 v92, v0
	v_mov_b32_e32 v93, v0
	v_mov_b32_e32 v94, v0
	v_mov_b32_e32 v95, v0
	v_mov_b32_e32 v88, v0
	v_mov_b32_e32 v89, v0
	v_mov_b32_e32 v90, v0
	v_mov_b32_e32 v91, v0
	v_mov_b32_e32 v108, v0
	v_mov_b32_e32 v109, v0
	v_mov_b32_e32 v110, v0
	v_mov_b32_e32 v111, v0
	v_mov_b32_e32 v104, v0
	v_mov_b32_e32 v105, v0
	v_mov_b32_e32 v106, v0
	v_mov_b32_e32 v107, v0
	v_mov_b32_e32 v124, v0
	v_mov_b32_e32 v125, v0
	v_mov_b32_e32 v126, v0
	v_mov_b32_e32 v127, v0
	v_mov_b32_e32 v120, v0
	v_mov_b32_e32 v121, v0
	v_mov_b32_e32 v122, v0
	v_mov_b32_e32 v123, v0
	.p2align 6
	s_nop 0
	s_nop 0

; template <class Epi, class Sched, bool ALIGN_EPI = false, bool SP2 = false>
; __device__ __forceinline__ void gemm_phase(PG8_LAS unsigned char* lds, const Gemm g, const Sched& S, const Epi& E, const int wid_in) {
;     ...
;         for (int t = 0; t < nt; t += 2) {
;             const bool last = (t == nt - 2);
;             const char* a1 = cA + (size_t)(t + 1) * kstep;
;             const char* a2 = last ? nA : cA + (size_t)(t + 2) * kstep; const char* b2 = last ? nB : cB + (size_t)(t + 2) * kstep;
;             const char* a3 = a2 + kstep; const char* b3 = b2 + kstep;
;     ...
; #pragma unroll
;         for (int a = 0; a < 2; ++a)
; #pragma unroll
;             for (int b = 0; b < 2; ++b)
; #pragma unroll
;                 for (int m = 0; m < 4; ++m)
; #pragma unroll
;                     for (int n = 0; n < 2; ++n) acc[a][b][m][n] = (f32x4){0.f, 0.f, 0.f, 0.f};
;         cur = nxt; cA = nA; cB = nB; ++ui;
.LBB0_1226:
	v_mov_b32_e32 v127, 0
	s_and_b64 vcc, exec, s[0:1]
	v_mov_b32_e32 v126, v127
	v_mov_b32_e32 v125, v127
	v_mov_b32_e32 v124, v127
	v_mov_b32_e32 v123, v127
	v_mov_b32_e32 v122, v127
	v_mov_b32_e32 v121, v127
	v_mov_b32_e32 v120, v127
	v_mov_b32_e32 v111, v127
	v_mov_b32_e32 v110, v127
	v_mov_b32_e32 v109, v127
	v_mov_b32_e32 v108, v127
	v_mov_b32_e32 v107, v127
	v_mov_b32_e32 v106, v127
	v_mov_b32_e32 v105, v127
	v_mov_b32_e32 v104, v127
	v_mov_b32_e32 v95, v127
	v_mov_b32_e32 v94, v127
	v_mov_b32_e32 v93, v127
	v_mov_b32_e32 v92, v127
	v_mov_b32_e32 v91, v127
	v_mov_b32_e32 v90, v127
	v_mov_b32_e32 v89, v127
	v_mov_b32_e32 v88, v127
	v_mov_b32_e32 v79, v127
	v_mov_b32_e32 v78, v127
	v_mov_b32_e32 v77, v127
	v_mov_b32_e32 v76, v127
	v_mov_b32_e32 v75, v127
	v_mov_b32_e32 v74, v127
	v_mov_b32_e32 v73, v127
	v_mov_b32_e32 v72, v127
	v_mov_b32_e32 v119, v127
	v_mov_b32_e32 v118, v127
	v_mov_b32_e32 v117, v127
	v_mov_b32_e32 v116, v127
	v_mov_b32_e32 v115, v127
	v_mov_b32_e32 v114, v127
	v_mov_b32_e32 v113, v127
	v_mov_b32_e32 v112, v127
	v_mov_b32_e32 v103, v127
	v_mov_b32_e32 v102, v127
	v_mov_b32_e32 v101, v127
	v_mov_b32_e32 v100, v127
	v_mov_b32_e32 v99, v127
	v_mov_b32_e32 v98, v127
	v_mov_b32_e32 v97, v127
	v_mov_b32_e32 v96, v127
	v_mov_b32_e32 v87, v127
	v_mov_b32_e32 v86, v127
	v_mov_b32_e32 v85, v127
	v_mov_b32_e32 v84, v127
	v_mov_b32_e32 v83, v127
	v_mov_b32_e32 v82, v127
	v_mov_b32_e32 v81, v127
	v_mov_b32_e32 v80, v127
	v_mov_b32_e32 v71, v127
	v_mov_b32_e32 v70, v127
	v_mov_b32_e32 v69, v127
	v_mov_b32_e32 v68, v127
	v_mov_b32_e32 v67, v127
	v_mov_b32_e32 v66, v127
	v_mov_b32_e32 v65, v127
	v_mov_b32_e32 v64, v127
	v_mov_b32_e32 v63, v127
	v_mov_b32_e32 v62, v127
	v_mov_b32_e32 v61, v127
	v_mov_b32_e32 v60, v127
	v_mov_b32_e32 v59, v127
	v_mov_b32_e32 v58, v127
	v_mov_b32_e32 v57, v127
	v_mov_b32_e32 v56, v127
	v_mov_b32_e32 v47, v127
	v_mov_b32_e32 v46, v127
	v_mov_b32_e32 v45, v127
	v_mov_b32_e32 v44, v127
	v_mov_b32_e32 v43, v127
	v_mov_b32_e32 v42, v127
	v_mov_b32_e32 v41, v127
	v_mov_b32_e32 v40, v127
	v_mov_b32_e32 v31, v127
	v_mov_b32_e32 v30, v127
	v_mov_b32_e32 v29, v127
	v_mov_b32_e32 v28, v127
	v_mov_b32_e32 v27, v127
	v_mov_b32_e32 v26, v127
	v_mov_b32_e32 v25, v127
	v_mov_b32_e32 v24, v127
	v_mov_b32_e32 v15, v127
	v_mov_b32_e32 v14, v127
	v_mov_b32_e32 v13, v127
	v_mov_b32_e32 v12, v127
	v_mov_b32_e32 v11, v127
	v_mov_b32_e32 v10, v127
	v_mov_b32_e32 v9, v127
	v_mov_b32_e32 v8, v127
	v_mov_b32_e32 v55, v127
	v_mov_b32_e32 v54, v127
	v_mov_b32_e32 v53, v127
	v_mov_b32_e32 v52, v127
	v_mov_b32_e32 v51, v127
	v_mov_b32_e32 v50, v127
	v_mov_b32_e32 v49, v127
	v_mov_b32_e32 v48, v127
	v_mov_b32_e32 v39, v127
	v_mov_b32_e32 v38, v127
	v_mov_b32_e32 v37, v127
	v_mov_b32_e32 v36, v127
	v_mov_b32_e32 v35, v127
	v_mov_b32_e32 v34, v127
	v_mov_b32_e32 v33, v127
	v_mov_b32_e32 v32, v127
	v_mov_b32_e32 v23, v127
	v_mov_b32_e32 v22, v127
	v_mov_b32_e32 v21, v127
	v_mov_b32_e32 v20, v127
	v_mov_b32_e32 v19, v127
	v_mov_b32_e32 v18, v127
	v_mov_b32_e32 v17, v127
	v_mov_b32_e32 v16, v127
	v_mov_b32_e32 v7, v127
	v_mov_b32_e32 v6, v127
	v_mov_b32_e32 v5, v127
	v_mov_b32_e32 v4, v127
	v_mov_b32_e32 v3, v127
	v_mov_b32_e32 v2, v127
	v_mov_b32_e32 v1, v127
	v_mov_b32_e32 v0, v127
	s_cbranch_vccnz .LBB0_1229
	s_add_u32 s24, s24, 0x80
	s_addc_u32 s25, s25, 0
	s_add_u32 s49, s26, 0x100
	v_mov_b32_e32 v0, 0
	s_addc_u32 s50, s27, 0
	s_mov_b32 s26, 0
	v_mov_b32_e32 v1, v0
	v_mov_b32_e32 v2, v0
	v_mov_b32_e32 v3, v0
	v_mov_b32_e32 v4, v0
	v_mov_b32_e32 v5, v0
	v_mov_b32_e32 v6, v0
	v_mov_b32_e32 v7, v0
	v_mov_b32_e32 v16, v0
	v_mov_b32_e32 v17, v0
	v_mov_b32_e32 v18, v0
	v_mov_b32_e32 v19, v0
	v_mov_b32_e32 v20, v0
	v_mov_b32_e32 v21, v0
	v_mov_b32_e32 v22, v0
	v_mov_b32_e32 v23, v0
	v_mov_b32_e32 v32, v0
	v_mov_b32_e32 v33, v0
	v_mov_b32_e32 v34, v0
	v_mov_b32_e32 v35, v0
	v_mov_b32_e32 v36, v0
	v_mov_b32_e32 v37, v0
	v_mov_b32_e32 v38, v0
	v_mov_b32_e32 v39, v0
	v_mov_b32_e32 v48, v0
	v_mov_b32_e32 v49, v0
	v_mov_b32_e32 v50, v0
	v_mov_b32_e32 v51, v0
	v_mov_b32_e32 v52, v0
	v_mov_b32_e32 v53, v0
	v_mov_b32_e32 v54, v0
	v_mov_b32_e32 v55, v0
	v_mov_b32_e32 v8, v0
	v_mov_b32_e32 v9, v0
	v_mov_b32_e32 v10, v0
	v_mov_b32_e32 v11, v0
	v_mov_b32_e32 v12, v0
	v_mov_b32_e32 v13, v0
	v_mov_b32_e32 v14, v0
	v_mov_b32_e32 v15, v0
	v_mov_b32_e32 v24, v0
	v_mov_b32_e32 v25, v0
	v_mov_b32_e32 v26, v0
	v_mov_b32_e32 v27, v0
	v_mov_b32_e32 v28, v0
	v_mov_b32_e32 v29, v0
	v_mov_b32_e32 v30, v0
	v_mov_b32_e32 v31, v0
	v_mov_b32_e32 v40, v0
	v_mov_b32_e32 v41, v0
	v_mov_b32_e32 v42, v0
	v_mov_b32_e32 v43, v0
	v_mov_b32_e32 v44, v0
	v_mov_b32_e32 v45, v0
	v_mov_b32_e32 v46, v0
	v_mov_b32_e32 v47, v0
	v_mov_b32_e32 v56, v0
	v_mov_b32_e32 v57, v0
	v_mov_b32_e32 v58, v0
	v_mov_b32_e32 v59, v0
	v_mov_b32_e32 v60, v0
	v_mov_b32_e32 v61, v0
	v_mov_b32_e32 v62, v0
	v_mov_b32_e32 v63, v0
	v_mov_b32_e32 v64, v0
	v_mov_b32_e32 v65, v0
	v_mov_b32_e32 v66, v0
	v_mov_b32_e32 v67, v0
	v_mov_b32_e32 v68, v0
	v_mov_b32_e32 v69, v0
	v_mov_b32_e32 v70, v0
	v_mov_b32_e32 v71, v0
	v_mov_b32_e32 v80, v0
	v_mov_b32_e32 v81, v0
	v_mov_b32_e32 v82, v0
	v_mov_b32_e32 v83, v0
	v_mov_b32_e32 v84, v0
	v_mov_b32_e32 v85, v0
	v_mov_b32_e32 v86, v0
	v_mov_b32_e32 v87, v0
	v_mov_b32_e32 v96, v0
	v_mov_b32_e32 v97, v0
	v_mov_b32_e32 v98, v0
	v_mov_b32_e32 v99, v0
	v_mov_b32_e32 v100, v0
	v_mov_b32_e32 v101, v0
	v_mov_b32_e32 v102, v0
	v_mov_b32_e32 v103, v0
	v_mov_b32_e32 v112, v0
	v_mov_b32_e32 v113, v0
	v_mov_b32_e32 v114, v0
	v_mov_b32_e32 v115, v0
	v_mov_b32_e32 v116, v0
	v_mov_b32_e32 v117, v0
	v_mov_b32_e32 v118, v0
	v_mov_b32_e32 v119, v0
	v_mov_b32_e32 v72, v0
	v_mov_b32_e32 v73, v0
	v_mov_b32_e32 v74, v0
	v_mov_b32_e32 v75, v0
	v_mov_b32_e32 v76, v0
	v_mov_b32_e32 v77, v0
	v_mov_b32_e32 v78, v0
	v_mov_b32_e32 v79, v0
	v_mov_b32_e32 v88, v0
	v_mov_b32_e32 v89, v0
	v_mov_b32_e32 v90, v0
	v_mov_b32_e32 v91, v0
	v_mov_b32_e32 v92, v0
	v_mov_b32_e32 v93, v0
	v_mov_b32_e32 v94, v0
	v_mov_b32_e32 v95, v0
	v_mov_b32_e32 v104, v0
	v_mov_b32_e32 v105, v0
	v_mov_b32_e32 v106, v0
	v_mov_b32_e32 v107, v0
	v_mov_b32_e32 v108, v0
	v_mov_b32_e32 v109, v0
	v_mov_b32_e32 v110, v0
	v_mov_b32_e32 v111, v0
	v_mov_b32_e32 v120, v0
	v_mov_b32_e32 v121, v0
	v_mov_b32_e32 v122, v0
	v_mov_b32_e32 v123, v0
	v_mov_b32_e32 v124, v0
	v_mov_b32_e32 v125, v0
	v_mov_b32_e32 v126, v0
	v_mov_b32_e32 v127, v0
	.p2align 6
	s_nop 0
	s_nop 0
	s_nop 0
	s_nop 0
	s_nop 0
	s_nop 0
	s_nop 0
	s_nop 0
	s_nop 0
	s_nop 0
	s_nop 0
	s_nop 0
